# nt also on the read-once loads of the residual epilogues (h_old rows in out-proj/down, h_old + PLE-projection rows in the PLE-gate epilogue)
# speedup vs baseline: 1.0034x; 1.0016x over previous
;     __device__ __forceinline__ void operator()(const f32x4 (&acc)[2][2][4][2], const pg8::Unit& u, int wr, int wc, int fr_, int fq_, LAS const unsigned char* xl) const {
;     ...
;         } else {
;             const int col = u.pn * 256 + wc * 32 + 8 * fq;
;             constexpr int MB = (MODE == 4) ? 2 : 4;
; #pragma unroll
;             for (int ai = 0; ai < 2; ++ai)
; #pragma unroll
;             for (int mb = 0; mb < 4; mb += MB) {
;                 u32x4 hw[MB][2], pw[MB][2];
; #pragma unroll
;                 for (int m = 0; m < MB; ++m)
; #pragma unroll
;                     for (int bj = 0; bj < 2; ++bj) { const size_t off = (size_t)(row0 + ai * 128 + (mb + m) * 16) * DM + col + bj * 128;
;                         hw[m][bj] = *(const u32x4*)(h_old + off); if (MODE == 4) pw[m][bj] = *(const u32x4*)(pp + off); }
; #pragma unroll
;                 for (int mm = 0; mm < MB; ++mm) {
;                     const int m = mb + mm;
;                     const int row = row0 + ai * 128 + m * 16; const float rinv = rv[ai][m];
;                     float ss = 0.f;
; #pragma unroll
;                     for (int bj = 0; bj < 2; ++bj) { const size_t off = (size_t)row * DM + col + bj * 128;
;                         const u32x4 h4 = hw[mm][bj];
;                         f32x4 a = {bf_lo(h4.x), bf_hi(h4.x), bf_lo(h4.y), bf_hi(h4.y)}, b = {bf_lo(h4.z), bf_hi(h4.z), bf_lo(h4.w), bf_hi(h4.w)};
;                         f32x4 d0 = acc[ai][bj][m][0], d1 = acc[ai][bj][m][1];
;                         if (MODE == 4) { const u32x4 p4 = pw[mm][bj];
;                             d0[0] = fast_sigmoid(d0[0] * rinv) * bf_lo(p4.x); d0[1] = fast_sigmoid(d0[1] * rinv) * bf_hi(p4.x);
;                             d0[2] = fast_sigmoid(d0[2] * rinv) * bf_lo(p4.y); d0[3] = fast_sigmoid(d0[3] * rinv) * bf_hi(p4.y);
;                             d1[0] = fast_sigmoid(d1[0] * rinv) * bf_lo(p4.z); d1[1] = fast_sigmoid(d1[1] * rinv) * bf_hi(p4.z);
;                             d1[2] = fast_sigmoid(d1[2] * rinv) * bf_lo(p4.w); d1[3] = fast_sigmoid(d1[3] * rinv) * bf_hi(p4.w); }
;                         a += d0; b += d1;
;                         u32x4 w; w.x = pg8::cvt_pk_bf16(a[0], a[1]); w.y = pg8::cvt_pk_bf16(a[2], a[3]); w.z = pg8::cvt_pk_bf16(b[0], b[1]); w.w = pg8::cvt_pk_bf16(b[2], b[3]);
;                         *(u32x4*)(O + off) = w;
.LBB0_356:
	s_lshl_b32 s0, s49, 8
	s_add_i32 s0, s0, s41
	v_readlane_b32 s28, v255, 24
	v_readlane_b32 s29, v255, 25
	v_add_u32_e32 v200, s0, v184
	s_lshl_b32 s0, s2, 8
	s_or_b32 s0, s0, s42
	v_lshl_add_u32 v201, v185, 3, s0
	v_lshlrev_b32_e32 v202, 11, v200
	v_lshl_or_b32 v202, v201, 1, v202
	v_mov_b32_e32 v203, 0
	s_mov_b32 s100, 0x8000
	s_mov_b32 s101, 0
	s_lshl_b32 s0, s2, 4
	s_lshl_b32 s86, s39, 2
	s_add_i32 s86, s86, s0
	s_mov_b32 s0, 0x28000
	s_mov_b32 s1, 0
	v_lshl_add_u64 v[194:195], s[28:29], 0, v[202:203]
	global_load_dwordx4 v[128:131], v[194:195], off nt
	global_load_dwordx4 v[132:135], v[194:195], off offset:256 nt
	v_lshl_add_u64 v[166:167], v[194:195], 0, s[100:101]
	global_load_dwordx4 v[136:139], v[166:167], off nt
	global_load_dwordx4 v[140:143], v[166:167], off offset:256 nt
	v_lshl_add_u64 v[194:195], v[166:167], 0, s[100:101]
	global_load_dwordx4 v[144:147], v[194:195], off nt
	global_load_dwordx4 v[148:151], v[194:195], off offset:256 nt
	v_lshl_add_u64 v[166:167], v[194:195], 0, s[100:101]
	global_load_dwordx4 v[152:155], v[166:167], off nt
	global_load_dwordx4 v[168:171], v[166:167], off offset:256 nt
	v_lshl_add_u64 v[194:195], v[166:167], 0, s[0:1]
	global_load_dwordx4 v[172:175], v[194:195], off nt
	global_load_dwordx4 v[176:179], v[194:195], off offset:256 nt
	v_lshl_add_u64 v[166:167], v[194:195], 0, s[100:101]
	global_load_dwordx4 v[180:183], v[166:167], off nt
	global_load_dwordx4 v[188:191], v[166:167], off offset:256 nt
	v_lshl_add_u64 v[194:195], v[166:167], 0, s[100:101]
	global_load_dwordx4 v[204:207], v[194:195], off nt
	global_load_dwordx4 v[208:211], v[194:195], off offset:256 nt
	v_lshl_add_u64 v[166:167], v[194:195], 0, s[100:101]
	v_lshlrev_b32_e32 v200, 6, v200
	v_add_u32_e32 v200, s86, v200
	v_mov_b32_e32 v201, 0
	v_lshl_add_u64 v[200:201], s[10:11], 0, v[200:201]
	v_lshl_add_u64 v[194:195], s[28:29], 0, v[202:203]
	s_waitcnt vmcnt(12)
	v_lshlrev_b32_e32 v212, 16, v128
	v_lshlrev_b32_e32 v213, 16, v129
	v_lshlrev_b32_e32 v214, 16, v130
	v_lshlrev_b32_e32 v215, 16, v131
	v_lshlrev_b32_e32 v216, 16, v132
	v_lshlrev_b32_e32 v217, 16, v133
	v_lshlrev_b32_e32 v218, 16, v134
	v_lshlrev_b32_e32 v219, 16, v135
	v_and_b32_e32 v128, 0xffff0000, v128
	v_and_b32_e32 v129, 0xffff0000, v129
	v_and_b32_e32 v130, 0xffff0000, v130
	v_and_b32_e32 v131, 0xffff0000, v131
	v_and_b32_e32 v132, 0xffff0000, v132
	v_and_b32_e32 v133, 0xffff0000, v133
	v_and_b32_e32 v134, 0xffff0000, v134
	v_and_b32_e32 v135, 0xffff0000, v135
	v_add_f32_e32 v120, v120, v212
	v_add_f32_e32 v121, v121, v128
	v_add_f32_e32 v122, v122, v213
	v_add_f32_e32 v123, v123, v129
	v_add_f32_e32 v124, v124, v214
	v_add_f32_e32 v125, v125, v130
	v_add_f32_e32 v126, v126, v215
	v_add_f32_e32 v127, v127, v131
	v_add_f32_e32 v116, v116, v216
	v_add_f32_e32 v117, v117, v132
	v_add_f32_e32 v118, v118, v217
	v_add_f32_e32 v119, v119, v133
	v_add_f32_e32 v112, v112, v218
	v_add_f32_e32 v113, v113, v134
	v_add_f32_e32 v114, v114, v219
	v_add_f32_e32 v115, v115, v135
	v_mul_f32_e32 v212, v120, v120
	v_mul_f32_e32 v213, v124, v124
	v_mul_f32_e32 v214, v116, v116
	v_mul_f32_e32 v215, v112, v112
	v_fmac_f32_e32 v212, v121, v121
	v_fmac_f32_e32 v213, v125, v125
	v_fmac_f32_e32 v214, v117, v117
	v_fmac_f32_e32 v215, v113, v113
	v_fmac_f32_e32 v212, v122, v122
	v_fmac_f32_e32 v213, v126, v126
	v_fmac_f32_e32 v214, v118, v118
	v_fmac_f32_e32 v215, v114, v114
	v_fmac_f32_e32 v212, v123, v123
	v_fmac_f32_e32 v213, v127, v127
	v_fmac_f32_e32 v214, v119, v119
	v_fmac_f32_e32 v215, v115, v115
	v_cvt_pk_bf16_f32 v120, v120, v121
	v_cvt_pk_bf16_f32 v121, v122, v123
	v_cvt_pk_bf16_f32 v122, v124, v125
	v_cvt_pk_bf16_f32 v123, v126, v127
	v_cvt_pk_bf16_f32 v116, v116, v117
	v_cvt_pk_bf16_f32 v117, v118, v119
	v_cvt_pk_bf16_f32 v118, v112, v113
	v_cvt_pk_bf16_f32 v119, v114, v115
	global_store_dwordx4 v[194:195], v[120:123], off
	global_store_dwordx4 v[194:195], v[116:119], off offset:256
	v_add_f32_e32 v212, v212, v213
	v_add_f32_e32 v214, v214, v215
	v_add_f32_e32 v124, v212, v214
	global_load_dwordx4 v[212:215], v[166:167], off nt
	global_load_dwordx4 v[216:219], v[166:167], off offset:256 nt
	v_lshl_add_u64 v[166:167], v[194:195], 0, s[100:101]
	s_waitcnt vmcnt(14)
	v_lshlrev_b32_e32 v128, 16, v136
	v_lshlrev_b32_e32 v129, 16, v137
	v_lshlrev_b32_e32 v130, 16, v138
	v_lshlrev_b32_e32 v131, 16, v139
	v_lshlrev_b32_e32 v132, 16, v140
	v_lshlrev_b32_e32 v133, 16, v141
	v_lshlrev_b32_e32 v134, 16, v142
	v_lshlrev_b32_e32 v135, 16, v143
	v_and_b32_e32 v136, 0xffff0000, v136
	v_and_b32_e32 v137, 0xffff0000, v137
	v_and_b32_e32 v138, 0xffff0000, v138
	v_and_b32_e32 v139, 0xffff0000, v139
	v_and_b32_e32 v140, 0xffff0000, v140
	v_and_b32_e32 v141, 0xffff0000, v141
	v_and_b32_e32 v142, 0xffff0000, v142
	v_and_b32_e32 v143, 0xffff0000, v143
	v_add_f32_e32 v108, v108, v128
	v_add_f32_e32 v109, v109, v136
	v_add_f32_e32 v110, v110, v129
	v_add_f32_e32 v111, v111, v137
	v_add_f32_e32 v104, v104, v130
	v_add_f32_e32 v105, v105, v138
	v_add_f32_e32 v106, v106, v131
	v_add_f32_e32 v107, v107, v139
	v_add_f32_e32 v100, v100, v132
	v_add_f32_e32 v101, v101, v140
	v_add_f32_e32 v102, v102, v133
	v_add_f32_e32 v103, v103, v141
	v_add_f32_e32 v96, v96, v134
	v_add_f32_e32 v97, v97, v142
	v_add_f32_e32 v98, v98, v135
	v_add_f32_e32 v99, v99, v143
	v_mul_f32_e32 v128, v108, v108
	v_mul_f32_e32 v129, v104, v104
	v_mul_f32_e32 v130, v100, v100
	v_mul_f32_e32 v131, v96, v96
	v_fmac_f32_e32 v128, v109, v109
	v_fmac_f32_e32 v129, v105, v105
	v_fmac_f32_e32 v130, v101, v101
	v_fmac_f32_e32 v131, v97, v97
	v_fmac_f32_e32 v128, v110, v110
	v_fmac_f32_e32 v129, v106, v106
	v_fmac_f32_e32 v130, v102, v102
	v_fmac_f32_e32 v131, v98, v98
	v_fmac_f32_e32 v128, v111, v111
	v_fmac_f32_e32 v129, v107, v107
	v_fmac_f32_e32 v130, v103, v103
	v_fmac_f32_e32 v131, v99, v99
	v_cvt_pk_bf16_f32 v108, v108, v109
	v_cvt_pk_bf16_f32 v109, v110, v111
	v_cvt_pk_bf16_f32 v110, v104, v105
	v_cvt_pk_bf16_f32 v111, v106, v107
	v_cvt_pk_bf16_f32 v100, v100, v101
	v_cvt_pk_bf16_f32 v101, v102, v103
	v_cvt_pk_bf16_f32 v102, v96, v97
	v_cvt_pk_bf16_f32 v103, v98, v99
	global_store_dwordx4 v[166:167], v[108:111], off
	global_store_dwordx4 v[166:167], v[100:103], off offset:256
	v_add_f32_e32 v128, v128, v129
	v_add_f32_e32 v130, v130, v131
	v_add_f32_e32 v104, v128, v130
	v_lshl_add_u64 v[194:195], v[166:167], 0, s[100:101]
	s_waitcnt vmcnt(14)
; __device__ __forceinline__ unsigned cvt_pk_bf16(float lo, float hi) { unsigned r; asm volatile("v_cvt_pk_bf16_f32 %0, %1, %2" : "=v"(r) : "v"(lo), "v"(hi)); return r; }
; __device__ __forceinline__ float bf_lo(unsigned w) { return __uint_as_float(w << 16); }
; __device__ __forceinline__ float bf_hi(unsigned w) { return __uint_as_float(w & 0xffff0000u); }
; __device__ __forceinline__ float fast_sigmoid(float x) { return __builtin_amdgcn_rcpf(1.0f + __expf(-x)); }
;     __device__ __forceinline__ void operator()(const f32x4 (&acc)[2][2][4][2], const pg8::Unit& u, int wr, int wc, int fr_, int fq_, LAS const unsigned char* xl) const {
;     ...
;                 for (int mm = 0; mm < MB; ++mm) {
;                     const int m = mb + mm;
;                     const int row = row0 + ai * 128 + m * 16; const float rinv = rv[ai][m];
;                     float ss = 0.f;
; #pragma unroll
;                     for (int bj = 0; bj < 2; ++bj) { const size_t off = (size_t)row * DM + col + bj * 128;
;                         const u32x4 h4 = hw[mm][bj];
;                         f32x4 a = {bf_lo(h4.x), bf_hi(h4.x), bf_lo(h4.y), bf_hi(h4.y)}, b = {bf_lo(h4.z), bf_hi(h4.z), bf_lo(h4.w), bf_hi(h4.w)};
;                         f32x4 d0 = acc[ai][bj][m][0], d1 = acc[ai][bj][m][1];
;                         if (MODE == 4) { const u32x4 p4 = pw[mm][bj];
;                             d0[0] = fast_sigmoid(d0[0] * rinv) * bf_lo(p4.x); d0[1] = fast_sigmoid(d0[1] * rinv) * bf_hi(p4.x);
;                             d0[2] = fast_sigmoid(d0[2] * rinv) * bf_lo(p4.y); d0[3] = fast_sigmoid(d0[3] * rinv) * bf_hi(p4.y);
;                             d1[0] = fast_sigmoid(d1[0] * rinv) * bf_lo(p4.z); d1[1] = fast_sigmoid(d1[1] * rinv) * bf_hi(p4.z);
;                             d1[2] = fast_sigmoid(d1[2] * rinv) * bf_lo(p4.w); d1[3] = fast_sigmoid(d1[3] * rinv) * bf_hi(p4.w); }
;                         a += d0; b += d1;
;                         u32x4 w; w.x = pg8::cvt_pk_bf16(a[0], a[1]); w.y = pg8::cvt_pk_bf16(a[2], a[3]); w.z = pg8::cvt_pk_bf16(b[0], b[1]); w.w = pg8::cvt_pk_bf16(b[2], b[3]);
;                         *(u32x4*)(O + off) = w;
;                         ss += (a[0] * a[0] + a[1] * a[1]) + (a[2] * a[2] + a[3] * a[3]) + (b[0] * b[0] + b[1] * b[1]) + (b[2] * b[2] + b[3] * b[3]); }
	v_lshlrev_b32_e32 v136, 16, v144
	v_lshlrev_b32_e32 v137, 16, v145
	v_lshlrev_b32_e32 v138, 16, v146
	v_lshlrev_b32_e32 v139, 16, v147
	v_lshlrev_b32_e32 v140, 16, v148
	v_lshlrev_b32_e32 v141, 16, v149
	v_lshlrev_b32_e32 v142, 16, v150
	v_lshlrev_b32_e32 v143, 16, v151
	v_and_b32_e32 v144, 0xffff0000, v144
	v_and_b32_e32 v145, 0xffff0000, v145
	v_and_b32_e32 v146, 0xffff0000, v146
	v_and_b32_e32 v147, 0xffff0000, v147
	v_and_b32_e32 v148, 0xffff0000, v148
	v_and_b32_e32 v149, 0xffff0000, v149
	v_and_b32_e32 v150, 0xffff0000, v150
	v_and_b32_e32 v151, 0xffff0000, v151
	v_add_f32_e32 v92, v92, v136
	v_add_f32_e32 v93, v93, v144
	v_add_f32_e32 v94, v94, v137
	v_add_f32_e32 v95, v95, v145
	v_add_f32_e32 v88, v88, v138
	v_add_f32_e32 v89, v89, v146
	v_add_f32_e32 v90, v90, v139
	v_add_f32_e32 v91, v91, v147
	v_add_f32_e32 v84, v84, v140
	v_add_f32_e32 v85, v85, v148
	v_add_f32_e32 v86, v86, v141
	v_add_f32_e32 v87, v87, v149
	v_add_f32_e32 v80, v80, v142
	v_add_f32_e32 v81, v81, v150
	v_add_f32_e32 v82, v82, v143
	v_add_f32_e32 v83, v83, v151
	v_mul_f32_e32 v136, v92, v92
	v_mul_f32_e32 v137, v88, v88
	v_mul_f32_e32 v138, v84, v84
	v_mul_f32_e32 v139, v80, v80
	v_fmac_f32_e32 v136, v93, v93
	v_fmac_f32_e32 v137, v89, v89
	v_fmac_f32_e32 v138, v85, v85
	v_fmac_f32_e32 v139, v81, v81
	v_fmac_f32_e32 v136, v94, v94
	v_fmac_f32_e32 v137, v90, v90
	v_fmac_f32_e32 v138, v86, v86
	v_fmac_f32_e32 v139, v82, v82
	v_fmac_f32_e32 v136, v95, v95
	v_fmac_f32_e32 v137, v91, v91
	v_fmac_f32_e32 v138, v87, v87
	v_fmac_f32_e32 v139, v83, v83
	v_cvt_pk_bf16_f32 v92, v92, v93
	v_cvt_pk_bf16_f32 v93, v94, v95
	v_cvt_pk_bf16_f32 v94, v88, v89
	v_cvt_pk_bf16_f32 v95, v90, v91
	v_cvt_pk_bf16_f32 v84, v84, v85
	v_cvt_pk_bf16_f32 v85, v86, v87
	v_cvt_pk_bf16_f32 v86, v80, v81
	v_cvt_pk_bf16_f32 v87, v82, v83
	global_store_dwordx4 v[194:195], v[92:95], off
	global_store_dwordx4 v[194:195], v[84:87], off offset:256
	v_add_f32_e32 v136, v136, v137
	v_add_f32_e32 v138, v138, v139
	v_add_f32_e32 v88, v136, v138
	v_lshl_add_u64 v[166:167], v[194:195], 0, s[100:101]
	s_waitcnt vmcnt(14)
	v_lshlrev_b32_e32 v144, 16, v152
	v_lshlrev_b32_e32 v145, 16, v153
	v_lshlrev_b32_e32 v146, 16, v154
	v_lshlrev_b32_e32 v147, 16, v155
	v_lshlrev_b32_e32 v148, 16, v168
	v_lshlrev_b32_e32 v149, 16, v169
	v_lshlrev_b32_e32 v150, 16, v170
	v_lshlrev_b32_e32 v151, 16, v171
	v_and_b32_e32 v152, 0xffff0000, v152
	v_and_b32_e32 v153, 0xffff0000, v153
	v_and_b32_e32 v154, 0xffff0000, v154
	v_and_b32_e32 v155, 0xffff0000, v155
	v_and_b32_e32 v168, 0xffff0000, v168
	v_and_b32_e32 v169, 0xffff0000, v169
	v_and_b32_e32 v170, 0xffff0000, v170
	v_and_b32_e32 v171, 0xffff0000, v171
	v_add_f32_e32 v76, v76, v144
	v_add_f32_e32 v77, v77, v152
	v_add_f32_e32 v78, v78, v145
	v_add_f32_e32 v79, v79, v153
	v_add_f32_e32 v72, v72, v146
	v_add_f32_e32 v73, v73, v154
	v_add_f32_e32 v74, v74, v147
	v_add_f32_e32 v75, v75, v155
	v_add_f32_e32 v68, v68, v148
	v_add_f32_e32 v69, v69, v168
	v_add_f32_e32 v70, v70, v149
	v_add_f32_e32 v71, v71, v169
	v_add_f32_e32 v64, v64, v150
	v_add_f32_e32 v65, v65, v170
	v_add_f32_e32 v66, v66, v151
	v_add_f32_e32 v67, v67, v171
	v_mul_f32_e32 v144, v76, v76
	v_mul_f32_e32 v145, v72, v72
	v_mul_f32_e32 v146, v68, v68
	v_mul_f32_e32 v147, v64, v64
	v_fmac_f32_e32 v144, v77, v77
	v_fmac_f32_e32 v145, v73, v73
	v_fmac_f32_e32 v146, v69, v69
	v_fmac_f32_e32 v147, v65, v65
	v_fmac_f32_e32 v144, v78, v78
	v_fmac_f32_e32 v145, v74, v74
	v_fmac_f32_e32 v146, v70, v70
	v_fmac_f32_e32 v147, v66, v66
	v_fmac_f32_e32 v144, v79, v79
	v_fmac_f32_e32 v145, v75, v75
	v_fmac_f32_e32 v146, v71, v71
	v_fmac_f32_e32 v147, v67, v67
	v_cvt_pk_bf16_f32 v76, v76, v77
	v_cvt_pk_bf16_f32 v77, v78, v79
	v_cvt_pk_bf16_f32 v78, v72, v73
	v_cvt_pk_bf16_f32 v79, v74, v75
	v_cvt_pk_bf16_f32 v68, v68, v69
	v_cvt_pk_bf16_f32 v69, v70, v71
	v_cvt_pk_bf16_f32 v70, v64, v65
	v_cvt_pk_bf16_f32 v71, v66, v67
	global_store_dwordx4 v[166:167], v[76:79], off
	global_store_dwordx4 v[166:167], v[68:71], off offset:256
	v_add_f32_e32 v144, v144, v145
	v_add_f32_e32 v146, v146, v147
	v_add_f32_e32 v72, v144, v146
	v_lshl_add_u64 v[194:195], v[166:167], 0, s[0:1]
	s_waitcnt vmcnt(14)
	v_lshlrev_b32_e32 v152, 16, v172
	v_lshlrev_b32_e32 v153, 16, v173
	v_lshlrev_b32_e32 v154, 16, v174
	v_lshlrev_b32_e32 v155, 16, v175
	v_lshlrev_b32_e32 v168, 16, v176
	v_lshlrev_b32_e32 v169, 16, v177
	v_lshlrev_b32_e32 v170, 16, v178
	v_lshlrev_b32_e32 v171, 16, v179
	v_and_b32_e32 v172, 0xffff0000, v172
	v_and_b32_e32 v173, 0xffff0000, v173
	v_and_b32_e32 v174, 0xffff0000, v174
	v_and_b32_e32 v175, 0xffff0000, v175
	v_and_b32_e32 v176, 0xffff0000, v176
	v_and_b32_e32 v177, 0xffff0000, v177
	v_and_b32_e32 v178, 0xffff0000, v178
	v_and_b32_e32 v179, 0xffff0000, v179
	v_add_f32_e32 v60, v60, v152
	v_add_f32_e32 v61, v61, v172
	v_add_f32_e32 v62, v62, v153
	v_add_f32_e32 v63, v63, v173
	v_add_f32_e32 v56, v56, v154
	v_add_f32_e32 v57, v57, v174
	v_add_f32_e32 v58, v58, v155
	v_add_f32_e32 v59, v59, v175
	v_add_f32_e32 v52, v52, v168
	v_add_f32_e32 v53, v53, v176
	v_add_f32_e32 v54, v54, v169
	v_add_f32_e32 v55, v55, v177
	v_add_f32_e32 v48, v48, v170
	v_add_f32_e32 v49, v49, v178
	v_add_f32_e32 v50, v50, v171
	v_add_f32_e32 v51, v51, v179
	v_mul_f32_e32 v152, v60, v60
	v_mul_f32_e32 v153, v56, v56
	v_mul_f32_e32 v154, v52, v52
	v_mul_f32_e32 v155, v48, v48
	v_fmac_f32_e32 v152, v61, v61
	v_fmac_f32_e32 v153, v57, v57
	v_fmac_f32_e32 v154, v53, v53
	v_fmac_f32_e32 v155, v49, v49
	v_fmac_f32_e32 v152, v62, v62
	v_fmac_f32_e32 v153, v58, v58
	v_fmac_f32_e32 v154, v54, v54
	v_fmac_f32_e32 v155, v50, v50
	v_fmac_f32_e32 v152, v63, v63
	v_fmac_f32_e32 v153, v59, v59
	v_fmac_f32_e32 v154, v55, v55
	v_fmac_f32_e32 v155, v51, v51
	v_cvt_pk_bf16_f32 v60, v60, v61
	v_cvt_pk_bf16_f32 v61, v62, v63
	v_cvt_pk_bf16_f32 v62, v56, v57
	v_cvt_pk_bf16_f32 v63, v58, v59
	v_cvt_pk_bf16_f32 v52, v52, v53
	v_cvt_pk_bf16_f32 v53, v54, v55
	v_cvt_pk_bf16_f32 v54, v48, v49
	v_cvt_pk_bf16_f32 v55, v50, v51
	global_store_dwordx4 v[194:195], v[60:63], off
	global_store_dwordx4 v[194:195], v[52:55], off offset:256
	v_add_f32_e32 v152, v152, v153
	v_add_f32_e32 v154, v154, v155
	v_add_f32_e32 v56, v152, v154
	v_lshl_add_u64 v[166:167], v[194:195], 0, s[100:101]
	s_waitcnt vmcnt(14)
; __device__ __forceinline__ unsigned cvt_pk_bf16(float lo, float hi) { unsigned r; asm volatile("v_cvt_pk_bf16_f32 %0, %1, %2" : "=v"(r) : "v"(lo), "v"(hi)); return r; }
; __device__ __forceinline__ float bf_lo(unsigned w) { return __uint_as_float(w << 16); }
; __device__ __forceinline__ float bf_hi(unsigned w) { return __uint_as_float(w & 0xffff0000u); }
; __device__ __forceinline__ float fast_sigmoid(float x) { return __builtin_amdgcn_rcpf(1.0f + __expf(-x)); }
;     __device__ __forceinline__ void operator()(const f32x4 (&acc)[2][2][4][2], const pg8::Unit& u, int wr, int wc, int fr_, int fq_, LAS const unsigned char* xl) const {
;     ...
;                 for (int mm = 0; mm < MB; ++mm) {
;                     const int m = mb + mm;
;                     const int row = row0 + ai * 128 + m * 16; const float rinv = rv[ai][m];
;                     float ss = 0.f;
; #pragma unroll
;                     for (int bj = 0; bj < 2; ++bj) { const size_t off = (size_t)row * DM + col + bj * 128;
;                         const u32x4 h4 = hw[mm][bj];
;                         f32x4 a = {bf_lo(h4.x), bf_hi(h4.x), bf_lo(h4.y), bf_hi(h4.y)}, b = {bf_lo(h4.z), bf_hi(h4.z), bf_lo(h4.w), bf_hi(h4.w)};
;                         f32x4 d0 = acc[ai][bj][m][0], d1 = acc[ai][bj][m][1];
;                         if (MODE == 4) { const u32x4 p4 = pw[mm][bj];
;                             d0[0] = fast_sigmoid(d0[0] * rinv) * bf_lo(p4.x); d0[1] = fast_sigmoid(d0[1] * rinv) * bf_hi(p4.x);
;                             d0[2] = fast_sigmoid(d0[2] * rinv) * bf_lo(p4.y); d0[3] = fast_sigmoid(d0[3] * rinv) * bf_hi(p4.y);
;                             d1[0] = fast_sigmoid(d1[0] * rinv) * bf_lo(p4.z); d1[1] = fast_sigmoid(d1[1] * rinv) * bf_hi(p4.z);
;                             d1[2] = fast_sigmoid(d1[2] * rinv) * bf_lo(p4.w); d1[3] = fast_sigmoid(d1[3] * rinv) * bf_hi(p4.w); }
;                         a += d0; b += d1;
;                         u32x4 w; w.x = pg8::cvt_pk_bf16(a[0], a[1]); w.y = pg8::cvt_pk_bf16(a[2], a[3]); w.z = pg8::cvt_pk_bf16(b[0], b[1]); w.w = pg8::cvt_pk_bf16(b[2], b[3]);
;                         *(u32x4*)(O + off) = w;
;                         ss += (a[0] * a[0] + a[1] * a[1]) + (a[2] * a[2] + a[3] * a[3]) + (b[0] * b[0] + b[1] * b[1]) + (b[2] * b[2] + b[3] * b[3]); }
	v_lshlrev_b32_e32 v172, 16, v180
	v_lshlrev_b32_e32 v173, 16, v181
	v_lshlrev_b32_e32 v174, 16, v182
	v_lshlrev_b32_e32 v175, 16, v183
	v_lshlrev_b32_e32 v176, 16, v188
	v_lshlrev_b32_e32 v177, 16, v189
	v_lshlrev_b32_e32 v178, 16, v190
	v_lshlrev_b32_e32 v179, 16, v191
	v_and_b32_e32 v180, 0xffff0000, v180
	v_and_b32_e32 v181, 0xffff0000, v181
	v_and_b32_e32 v182, 0xffff0000, v182
	v_and_b32_e32 v183, 0xffff0000, v183
	v_and_b32_e32 v188, 0xffff0000, v188
	v_and_b32_e32 v189, 0xffff0000, v189
	v_and_b32_e32 v190, 0xffff0000, v190
	v_and_b32_e32 v191, 0xffff0000, v191
	v_add_f32_e32 v44, v44, v172
	v_add_f32_e32 v45, v45, v180
	v_add_f32_e32 v46, v46, v173
	v_add_f32_e32 v47, v47, v181
	v_add_f32_e32 v40, v40, v174
	v_add_f32_e32 v41, v41, v182
	v_add_f32_e32 v42, v42, v175
	v_add_f32_e32 v43, v43, v183
	v_add_f32_e32 v36, v36, v176
	v_add_f32_e32 v37, v37, v188
	v_add_f32_e32 v38, v38, v177
	v_add_f32_e32 v39, v39, v189
	v_add_f32_e32 v32, v32, v178
	v_add_f32_e32 v33, v33, v190
	v_add_f32_e32 v34, v34, v179
	v_add_f32_e32 v35, v35, v191
	v_mul_f32_e32 v172, v44, v44
	v_mul_f32_e32 v173, v40, v40
	v_mul_f32_e32 v174, v36, v36
	v_mul_f32_e32 v175, v32, v32
	v_fmac_f32_e32 v172, v45, v45
	v_fmac_f32_e32 v173, v41, v41
	v_fmac_f32_e32 v174, v37, v37
	v_fmac_f32_e32 v175, v33, v33
	v_fmac_f32_e32 v172, v46, v46
	v_fmac_f32_e32 v173, v42, v42
	v_fmac_f32_e32 v174, v38, v38
	v_fmac_f32_e32 v175, v34, v34
	v_fmac_f32_e32 v172, v47, v47
	v_fmac_f32_e32 v173, v43, v43
	v_fmac_f32_e32 v174, v39, v39
	v_fmac_f32_e32 v175, v35, v35
	v_cvt_pk_bf16_f32 v44, v44, v45
	v_cvt_pk_bf16_f32 v45, v46, v47
	v_cvt_pk_bf16_f32 v46, v40, v41
	v_cvt_pk_bf16_f32 v47, v42, v43
	v_cvt_pk_bf16_f32 v36, v36, v37
	v_cvt_pk_bf16_f32 v37, v38, v39
	v_cvt_pk_bf16_f32 v38, v32, v33
	v_cvt_pk_bf16_f32 v39, v34, v35
	global_store_dwordx4 v[166:167], v[44:47], off
	global_store_dwordx4 v[166:167], v[36:39], off offset:256
	v_add_f32_e32 v172, v172, v173
	v_add_f32_e32 v174, v174, v175
	v_add_f32_e32 v40, v172, v174
	v_lshl_add_u64 v[194:195], v[166:167], 0, s[100:101]
	s_waitcnt vmcnt(14)
	v_lshlrev_b32_e32 v180, 16, v204
	v_lshlrev_b32_e32 v181, 16, v205
	v_lshlrev_b32_e32 v182, 16, v206
	v_lshlrev_b32_e32 v183, 16, v207
	v_lshlrev_b32_e32 v188, 16, v208
	v_lshlrev_b32_e32 v189, 16, v209
	v_lshlrev_b32_e32 v190, 16, v210
	v_lshlrev_b32_e32 v191, 16, v211
	v_and_b32_e32 v204, 0xffff0000, v204
	v_and_b32_e32 v205, 0xffff0000, v205
	v_and_b32_e32 v206, 0xffff0000, v206
	v_and_b32_e32 v207, 0xffff0000, v207
	v_and_b32_e32 v208, 0xffff0000, v208
	v_and_b32_e32 v209, 0xffff0000, v209
	v_and_b32_e32 v210, 0xffff0000, v210
	v_and_b32_e32 v211, 0xffff0000, v211
	v_add_f32_e32 v28, v28, v180
	v_add_f32_e32 v29, v29, v204
	v_add_f32_e32 v30, v30, v181
	v_add_f32_e32 v31, v31, v205
	v_add_f32_e32 v24, v24, v182
	v_add_f32_e32 v25, v25, v206
	v_add_f32_e32 v26, v26, v183
	v_add_f32_e32 v27, v27, v207
	v_add_f32_e32 v20, v20, v188
	v_add_f32_e32 v21, v21, v208
	v_add_f32_e32 v22, v22, v189
	v_add_f32_e32 v23, v23, v209
	v_add_f32_e32 v16, v16, v190
	v_add_f32_e32 v17, v17, v210
	v_add_f32_e32 v18, v18, v191
	v_add_f32_e32 v19, v19, v211
	v_mul_f32_e32 v180, v28, v28
	v_mul_f32_e32 v181, v24, v24
	v_mul_f32_e32 v182, v20, v20
	v_mul_f32_e32 v183, v16, v16
	v_fmac_f32_e32 v180, v29, v29
	v_fmac_f32_e32 v181, v25, v25
	v_fmac_f32_e32 v182, v21, v21
	v_fmac_f32_e32 v183, v17, v17
	v_fmac_f32_e32 v180, v30, v30
	v_fmac_f32_e32 v181, v26, v26
	v_fmac_f32_e32 v182, v22, v22
	v_fmac_f32_e32 v183, v18, v18
	v_fmac_f32_e32 v180, v31, v31
	v_fmac_f32_e32 v181, v27, v27
	v_fmac_f32_e32 v182, v23, v23
	v_fmac_f32_e32 v183, v19, v19
	v_cvt_pk_bf16_f32 v28, v28, v29
	v_cvt_pk_bf16_f32 v29, v30, v31
	v_cvt_pk_bf16_f32 v30, v24, v25
	v_cvt_pk_bf16_f32 v31, v26, v27
	v_cvt_pk_bf16_f32 v20, v20, v21
	v_cvt_pk_bf16_f32 v21, v22, v23
	v_cvt_pk_bf16_f32 v22, v16, v17
	v_cvt_pk_bf16_f32 v23, v18, v19
	global_store_dwordx4 v[194:195], v[28:31], off
	global_store_dwordx4 v[194:195], v[20:23], off offset:256
	v_add_f32_e32 v180, v180, v181
	v_add_f32_e32 v182, v182, v183
	v_add_f32_e32 v24, v180, v182
	v_lshl_add_u64 v[166:167], v[194:195], 0, s[100:101]
	s_waitcnt vmcnt(12)
; __device__ __forceinline__ unsigned cvt_pk_bf16(float lo, float hi) { unsigned r; asm volatile("v_cvt_pk_bf16_f32 %0, %1, %2" : "=v"(r) : "v"(lo), "v"(hi)); return r; }
; __device__ __forceinline__ float bf_lo(unsigned w) { return __uint_as_float(w << 16); }
; __device__ __forceinline__ float bf_hi(unsigned w) { return __uint_as_float(w & 0xffff0000u); }
;     __device__ __forceinline__ void operator()(const f32x4 (&acc)[2][2][4][2], const pg8::Unit& u, int wr, int wc, int fr_, int fq_, LAS const unsigned char* xl) const {
;     ...
;                 for (int mm = 0; mm < MB; ++mm) {
;                     const int m = mb + mm;
;                     const int row = row0 + ai * 128 + m * 16; const float rinv = rv[ai][m];
;                     float ss = 0.f;
; #pragma unroll
;                     for (int bj = 0; bj < 2; ++bj) { const size_t off = (size_t)row * DM + col + bj * 128;
;                         const u32x4 h4 = hw[mm][bj];
;                         f32x4 a = {bf_lo(h4.x), bf_hi(h4.x), bf_lo(h4.y), bf_hi(h4.y)}, b = {bf_lo(h4.z), bf_hi(h4.z), bf_lo(h4.w), bf_hi(h4.w)};
;                         f32x4 d0 = acc[ai][bj][m][0], d1 = acc[ai][bj][m][1];
;                         if (MODE == 4) { const u32x4 p4 = pw[mm][bj];
;                             d0[0] = fast_sigmoid(d0[0] * rinv) * bf_lo(p4.x); d0[1] = fast_sigmoid(d0[1] * rinv) * bf_hi(p4.x);
;                             d0[2] = fast_sigmoid(d0[2] * rinv) * bf_lo(p4.y); d0[3] = fast_sigmoid(d0[3] * rinv) * bf_hi(p4.y);
;                             d1[0] = fast_sigmoid(d1[0] * rinv) * bf_lo(p4.z); d1[1] = fast_sigmoid(d1[1] * rinv) * bf_hi(p4.z);
;                             d1[2] = fast_sigmoid(d1[2] * rinv) * bf_lo(p4.w); d1[3] = fast_sigmoid(d1[3] * rinv) * bf_hi(p4.w); }
;                         a += d0; b += d1;
;                         u32x4 w; w.x = pg8::cvt_pk_bf16(a[0], a[1]); w.y = pg8::cvt_pk_bf16(a[2], a[3]); w.z = pg8::cvt_pk_bf16(b[0], b[1]); w.w = pg8::cvt_pk_bf16(b[2], b[3]);
;                         *(u32x4*)(O + off) = w;
;                         ss += (a[0] * a[0] + a[1] * a[1]) + (a[2] * a[2] + a[3] * a[3]) + (b[0] * b[0] + b[1] * b[1]) + (b[2] * b[2] + b[3] * b[3]); }
;                     ss = xrow16_sum(ss);
;                     if (fq == 0) part_out[(size_t)row * 16 + u.pn * 4 + wc] = ss;
;                 }
	v_lshlrev_b32_e32 v204, 16, v212
	v_lshlrev_b32_e32 v205, 16, v213
	v_lshlrev_b32_e32 v206, 16, v214
	v_lshlrev_b32_e32 v207, 16, v215
	v_lshlrev_b32_e32 v208, 16, v216
	v_lshlrev_b32_e32 v209, 16, v217
	v_lshlrev_b32_e32 v210, 16, v218
	v_lshlrev_b32_e32 v211, 16, v219
	v_and_b32_e32 v212, 0xffff0000, v212
	v_and_b32_e32 v213, 0xffff0000, v213
	v_and_b32_e32 v214, 0xffff0000, v214
	v_and_b32_e32 v215, 0xffff0000, v215
	v_and_b32_e32 v216, 0xffff0000, v216
	v_and_b32_e32 v217, 0xffff0000, v217
	v_and_b32_e32 v218, 0xffff0000, v218
	v_and_b32_e32 v219, 0xffff0000, v219
	v_add_f32_e32 v12, v12, v204
	v_add_f32_e32 v13, v13, v212
	v_add_f32_e32 v14, v14, v205
	v_add_f32_e32 v15, v15, v213
	v_add_f32_e32 v8, v8, v206
	v_add_f32_e32 v9, v9, v214
	v_add_f32_e32 v10, v10, v207
	v_add_f32_e32 v11, v11, v215
	v_add_f32_e32 v4, v4, v208
	v_add_f32_e32 v5, v5, v216
	v_add_f32_e32 v6, v6, v209
	v_add_f32_e32 v7, v7, v217
	v_add_f32_e32 v0, v0, v210
	v_add_f32_e32 v1, v1, v218
	v_add_f32_e32 v2, v2, v211
	v_add_f32_e32 v3, v3, v219
	v_mul_f32_e32 v204, v12, v12
	v_mul_f32_e32 v205, v8, v8
	v_mul_f32_e32 v206, v4, v4
	v_mul_f32_e32 v207, v0, v0
	v_fmac_f32_e32 v204, v13, v13
	v_fmac_f32_e32 v205, v9, v9
	v_fmac_f32_e32 v206, v5, v5
	v_fmac_f32_e32 v207, v1, v1
	v_fmac_f32_e32 v204, v14, v14
	v_fmac_f32_e32 v205, v10, v10
	v_fmac_f32_e32 v206, v6, v6
	v_fmac_f32_e32 v207, v2, v2
	v_fmac_f32_e32 v204, v15, v15
	v_fmac_f32_e32 v205, v11, v11
	v_fmac_f32_e32 v206, v7, v7
	v_fmac_f32_e32 v207, v3, v3
	v_cvt_pk_bf16_f32 v12, v12, v13
	v_cvt_pk_bf16_f32 v13, v14, v15
	v_cvt_pk_bf16_f32 v14, v8, v9
	v_cvt_pk_bf16_f32 v15, v10, v11
	v_cvt_pk_bf16_f32 v4, v4, v5
	v_cvt_pk_bf16_f32 v5, v6, v7
	v_cvt_pk_bf16_f32 v6, v0, v1
	v_cvt_pk_bf16_f32 v7, v2, v3
	global_store_dwordx4 v[166:167], v[12:15], off
	global_store_dwordx4 v[166:167], v[4:7], off offset:256
	v_add_f32_e32 v204, v204, v205
	v_add_f32_e32 v206, v206, v207
	v_add_f32_e32 v8, v204, v206
	v_mov_b32_e32 v125, v124
	v_mov_b32_e32 v105, v104
	v_mov_b32_e32 v89, v88
	v_mov_b32_e32 v73, v72
	v_mov_b32_e32 v57, v56
	v_mov_b32_e32 v41, v40
	v_mov_b32_e32 v25, v24
	v_mov_b32_e32 v9, v8
	v_permlane16_swap_b32_e32 v124, v125
	v_permlane16_swap_b32_e32 v104, v105
	v_permlane16_swap_b32_e32 v88, v89
	v_permlane16_swap_b32_e32 v72, v73
	v_permlane16_swap_b32_e32 v56, v57
	v_permlane16_swap_b32_e32 v40, v41
	v_permlane16_swap_b32_e32 v24, v25
	v_permlane16_swap_b32_e32 v8, v9
	v_add_f32_e32 v124, v124, v125
	v_add_f32_e32 v104, v104, v105
	v_add_f32_e32 v88, v88, v89
	v_add_f32_e32 v72, v72, v73
	v_add_f32_e32 v56, v56, v57
	v_add_f32_e32 v40, v40, v41
	v_add_f32_e32 v24, v24, v25
	v_add_f32_e32 v8, v8, v9
	v_mov_b32_e32 v125, v124
	v_mov_b32_e32 v105, v104
	v_mov_b32_e32 v89, v88
	v_mov_b32_e32 v73, v72
	v_mov_b32_e32 v57, v56
	v_mov_b32_e32 v41, v40
	v_mov_b32_e32 v25, v24
	v_mov_b32_e32 v9, v8
	v_permlane32_swap_b32_e32 v124, v125
	v_permlane32_swap_b32_e32 v104, v105
	v_permlane32_swap_b32_e32 v88, v89
	v_permlane32_swap_b32_e32 v72, v73
	v_permlane32_swap_b32_e32 v56, v57
	v_permlane32_swap_b32_e32 v40, v41
	v_permlane32_swap_b32_e32 v24, v25
	v_permlane32_swap_b32_e32 v8, v9
	v_add_f32_e32 v124, v124, v125
	v_add_f32_e32 v104, v104, v105
	v_add_f32_e32 v88, v88, v89
	v_add_f32_e32 v72, v72, v73
	v_add_f32_e32 v56, v56, v57
	v_add_f32_e32 v40, v40, v41
	v_add_f32_e32 v24, v24, v25
	v_add_f32_e32 v8, v8, v9
	s_mov_b32 s100, 0x2000
	v_cmp_eq_u32_e32 vcc, 0, v185
	v_lshl_add_u64 v[202:203], v[200:201], 0, s[100:101]
	s_and_saveexec_b64 s[28:29], vcc
	global_store_dword v[200:201], v124, off
	global_store_dword v[200:201], v104, off offset:1024
	global_store_dword v[200:201], v88, off offset:2048
	global_store_dword v[200:201], v72, off offset:3072
	global_store_dword v[202:203], v56, off
	global_store_dword v[202:203], v40, off offset:1024
	global_store_dword v[202:203], v24, off offset:2048
	global_store_dword v[202:203], v8, off offset:3072
	s_or_b64 exec, exec, s[28:29]
	s_and_b64 vcc, exec, s[6:7]
	s_mov_b64 s[0:1], -1
	s_cbranch_vccnz .LBB0_340
	s_andn2_b64 vcc, exec, s[20:21]
	s_cbranch_vccnz .LBB0_339
	s_barrier
	s_branch .LBB0_339

;     __device__ __forceinline__ void operator()(const f32x4 (&acc)[2][2][4][2], const pg8::Unit& u, int wr, int wc, int fr_, int fq_, LAS const unsigned char* xl) const {
;     ...
;         } else {
;             const int col = u.pn * 256 + wc * 32 + 8 * fq;
;             constexpr int MB = (MODE == 4) ? 2 : 4;
; #pragma unroll
;             for (int ai = 0; ai < 2; ++ai)
; #pragma unroll
;             for (int mb = 0; mb < 4; mb += MB) {
;                 u32x4 hw[MB][2], pw[MB][2];
; #pragma unroll
;                 for (int m = 0; m < MB; ++m)
; #pragma unroll
;                     for (int bj = 0; bj < 2; ++bj) { const size_t off = (size_t)(row0 + ai * 128 + (mb + m) * 16) * DM + col + bj * 128;
;                         hw[m][bj] = *(const u32x4*)(h_old + off); if (MODE == 4) pw[m][bj] = *(const u32x4*)(pp + off); }
; #pragma unroll
;                 for (int mm = 0; mm < MB; ++mm) {
;                     const int m = mb + mm;
;                     const int row = row0 + ai * 128 + m * 16; const float rinv = rv[ai][m];
;                     float ss = 0.f;
; #pragma unroll
;                     for (int bj = 0; bj < 2; ++bj) { const size_t off = (size_t)row * DM + col + bj * 128;
;                         const u32x4 h4 = hw[mm][bj];
;                         f32x4 a = {bf_lo(h4.x), bf_hi(h4.x), bf_lo(h4.y), bf_hi(h4.y)}, b = {bf_lo(h4.z), bf_hi(h4.z), bf_lo(h4.w), bf_hi(h4.w)};
;                         f32x4 d0 = acc[ai][bj][m][0], d1 = acc[ai][bj][m][1];
;                         if (MODE == 4) { const u32x4 p4 = pw[mm][bj];
;                             d0[0] = fast_sigmoid(d0[0] * rinv) * bf_lo(p4.x); d0[1] = fast_sigmoid(d0[1] * rinv) * bf_hi(p4.x);
;                             d0[2] = fast_sigmoid(d0[2] * rinv) * bf_lo(p4.y); d0[3] = fast_sigmoid(d0[3] * rinv) * bf_hi(p4.y);
;                             d1[0] = fast_sigmoid(d1[0] * rinv) * bf_lo(p4.z); d1[1] = fast_sigmoid(d1[1] * rinv) * bf_hi(p4.z);
;                             d1[2] = fast_sigmoid(d1[2] * rinv) * bf_lo(p4.w); d1[3] = fast_sigmoid(d1[3] * rinv) * bf_hi(p4.w); }
;                         a += d0; b += d1;
;                         u32x4 w; w.x = pg8::cvt_pk_bf16(a[0], a[1]); w.y = pg8::cvt_pk_bf16(a[2], a[3]); w.z = pg8::cvt_pk_bf16(b[0], b[1]); w.w = pg8::cvt_pk_bf16(b[2], b[3]);
;                         *(u32x4*)(O + off) = w;
.LBB0_500:
	s_lshl_b32 s0, s47, 8
	s_add_i32 s0, s0, s39
	v_readlane_b32 s26, v255, 24
	v_readlane_b32 s27, v255, 25
	v_readlane_b32 s48, v255, 26
	v_readlane_b32 s49, v255, 27
	v_add_u32_e32 v200, s0, v184
	s_lshl_b32 s0, s2, 8
	s_or_b32 s0, s0, s40
	v_lshl_add_u32 v201, v185, 3, s0
	v_lshlrev_b32_e32 v202, 11, v200
	v_lshl_or_b32 v202, v201, 1, v202
	v_mov_b32_e32 v203, 0
	s_mov_b32 s100, 0x8000
	s_mov_b32 s101, 0
	s_lshl_b32 s0, s2, 4
	s_lshl_b32 s86, s37, 2
	s_add_i32 s86, s86, s0
	s_mov_b32 s0, 0x28000
	s_mov_b32 s1, 0
	v_lshl_add_u64 v[194:195], s[26:27], 0, v[202:203]
	global_load_dwordx4 v[128:131], v[194:195], off nt
	global_load_dwordx4 v[132:135], v[194:195], off offset:256 nt
	v_lshl_add_u64 v[166:167], v[194:195], 0, s[100:101]
	global_load_dwordx4 v[136:139], v[166:167], off nt
	global_load_dwordx4 v[140:143], v[166:167], off offset:256 nt
	v_lshl_add_u64 v[194:195], v[166:167], 0, s[100:101]
	global_load_dwordx4 v[144:147], v[194:195], off nt
	global_load_dwordx4 v[148:151], v[194:195], off offset:256 nt
	v_lshl_add_u64 v[166:167], v[194:195], 0, s[100:101]
	global_load_dwordx4 v[152:155], v[166:167], off nt
	global_load_dwordx4 v[168:171], v[166:167], off offset:256 nt
	v_lshl_add_u64 v[194:195], v[166:167], 0, s[0:1]
	global_load_dwordx4 v[172:175], v[194:195], off nt
	global_load_dwordx4 v[176:179], v[194:195], off offset:256 nt
	v_lshl_add_u64 v[166:167], v[194:195], 0, s[100:101]
	global_load_dwordx4 v[180:183], v[166:167], off nt
	global_load_dwordx4 v[188:191], v[166:167], off offset:256 nt
	v_lshl_add_u64 v[194:195], v[166:167], 0, s[100:101]
	global_load_dwordx4 v[204:207], v[194:195], off nt
	global_load_dwordx4 v[208:211], v[194:195], off offset:256 nt
	v_lshl_add_u64 v[166:167], v[194:195], 0, s[100:101]
	v_lshlrev_b32_e32 v200, 6, v200
	v_add_u32_e32 v200, s86, v200
	v_mov_b32_e32 v201, 0
	v_lshl_add_u64 v[200:201], s[48:49], 0, v[200:201]
	v_lshl_add_u64 v[194:195], s[26:27], 0, v[202:203]
	s_waitcnt vmcnt(12)
	v_lshlrev_b32_e32 v212, 16, v128
	v_lshlrev_b32_e32 v213, 16, v129
	v_lshlrev_b32_e32 v214, 16, v130
	v_lshlrev_b32_e32 v215, 16, v131
	v_lshlrev_b32_e32 v216, 16, v132
	v_lshlrev_b32_e32 v217, 16, v133
	v_lshlrev_b32_e32 v218, 16, v134
	v_lshlrev_b32_e32 v219, 16, v135
	v_and_b32_e32 v128, 0xffff0000, v128
	v_and_b32_e32 v129, 0xffff0000, v129
	v_and_b32_e32 v130, 0xffff0000, v130
	v_and_b32_e32 v131, 0xffff0000, v131
	v_and_b32_e32 v132, 0xffff0000, v132
	v_and_b32_e32 v133, 0xffff0000, v133
	v_and_b32_e32 v134, 0xffff0000, v134
	v_and_b32_e32 v135, 0xffff0000, v135
	v_add_f32_e32 v120, v120, v212
	v_add_f32_e32 v121, v121, v128
	v_add_f32_e32 v122, v122, v213
	v_add_f32_e32 v123, v123, v129
	v_add_f32_e32 v124, v124, v214
	v_add_f32_e32 v125, v125, v130
	v_add_f32_e32 v126, v126, v215
	v_add_f32_e32 v127, v127, v131
	v_add_f32_e32 v116, v116, v216
	v_add_f32_e32 v117, v117, v132
	v_add_f32_e32 v118, v118, v217
	v_add_f32_e32 v119, v119, v133
	v_add_f32_e32 v112, v112, v218
	v_add_f32_e32 v113, v113, v134
	v_add_f32_e32 v114, v114, v219
	v_add_f32_e32 v115, v115, v135
	v_mul_f32_e32 v212, v120, v120
	v_mul_f32_e32 v213, v124, v124
	v_mul_f32_e32 v214, v116, v116
	v_mul_f32_e32 v215, v112, v112
	v_fmac_f32_e32 v212, v121, v121
	v_fmac_f32_e32 v213, v125, v125
	v_fmac_f32_e32 v214, v117, v117
	v_fmac_f32_e32 v215, v113, v113
	v_fmac_f32_e32 v212, v122, v122
	v_fmac_f32_e32 v213, v126, v126
	v_fmac_f32_e32 v214, v118, v118
	v_fmac_f32_e32 v215, v114, v114
	v_fmac_f32_e32 v212, v123, v123
	v_fmac_f32_e32 v213, v127, v127
	v_fmac_f32_e32 v214, v119, v119
	v_fmac_f32_e32 v215, v115, v115
	v_cvt_pk_bf16_f32 v120, v120, v121
	v_cvt_pk_bf16_f32 v121, v122, v123
	v_cvt_pk_bf16_f32 v122, v124, v125
	v_cvt_pk_bf16_f32 v123, v126, v127
	v_cvt_pk_bf16_f32 v116, v116, v117
	v_cvt_pk_bf16_f32 v117, v118, v119
	v_cvt_pk_bf16_f32 v118, v112, v113
	v_cvt_pk_bf16_f32 v119, v114, v115
	global_store_dwordx4 v[194:195], v[120:123], off
	global_store_dwordx4 v[194:195], v[116:119], off offset:256
	v_add_f32_e32 v212, v212, v213
	v_add_f32_e32 v214, v214, v215
	v_add_f32_e32 v124, v212, v214
	global_load_dwordx4 v[212:215], v[166:167], off nt
	global_load_dwordx4 v[216:219], v[166:167], off offset:256 nt
	v_lshl_add_u64 v[166:167], v[194:195], 0, s[100:101]
	s_waitcnt vmcnt(14)
	v_lshlrev_b32_e32 v128, 16, v136
	v_lshlrev_b32_e32 v129, 16, v137
	v_lshlrev_b32_e32 v130, 16, v138
	v_lshlrev_b32_e32 v131, 16, v139
	v_lshlrev_b32_e32 v132, 16, v140
	v_lshlrev_b32_e32 v133, 16, v141
	v_lshlrev_b32_e32 v134, 16, v142
	v_lshlrev_b32_e32 v135, 16, v143
	v_and_b32_e32 v136, 0xffff0000, v136
	v_and_b32_e32 v137, 0xffff0000, v137
	v_and_b32_e32 v138, 0xffff0000, v138
	v_and_b32_e32 v139, 0xffff0000, v139
	v_and_b32_e32 v140, 0xffff0000, v140
	v_and_b32_e32 v141, 0xffff0000, v141
	v_and_b32_e32 v142, 0xffff0000, v142
	v_and_b32_e32 v143, 0xffff0000, v143
	v_add_f32_e32 v108, v108, v128
	v_add_f32_e32 v109, v109, v136
	v_add_f32_e32 v110, v110, v129
	v_add_f32_e32 v111, v111, v137
	v_add_f32_e32 v104, v104, v130
	v_add_f32_e32 v105, v105, v138
	v_add_f32_e32 v106, v106, v131
	v_add_f32_e32 v107, v107, v139
	v_add_f32_e32 v100, v100, v132
	v_add_f32_e32 v101, v101, v140
	v_add_f32_e32 v102, v102, v133
	v_add_f32_e32 v103, v103, v141
	v_add_f32_e32 v96, v96, v134
	v_add_f32_e32 v97, v97, v142
	v_add_f32_e32 v98, v98, v135
	v_add_f32_e32 v99, v99, v143
	v_mul_f32_e32 v128, v108, v108
	v_mul_f32_e32 v129, v104, v104
	v_mul_f32_e32 v130, v100, v100
	v_mul_f32_e32 v131, v96, v96
	v_fmac_f32_e32 v128, v109, v109
	v_fmac_f32_e32 v129, v105, v105
	v_fmac_f32_e32 v130, v101, v101
	v_fmac_f32_e32 v131, v97, v97
	v_fmac_f32_e32 v128, v110, v110
	v_fmac_f32_e32 v129, v106, v106
	v_fmac_f32_e32 v130, v102, v102
	v_fmac_f32_e32 v131, v98, v98
	v_fmac_f32_e32 v128, v111, v111
	v_fmac_f32_e32 v129, v107, v107
	v_fmac_f32_e32 v130, v103, v103
	v_fmac_f32_e32 v131, v99, v99
	v_cvt_pk_bf16_f32 v108, v108, v109
	v_cvt_pk_bf16_f32 v109, v110, v111
	v_cvt_pk_bf16_f32 v110, v104, v105
	v_cvt_pk_bf16_f32 v111, v106, v107
	v_cvt_pk_bf16_f32 v100, v100, v101
	v_cvt_pk_bf16_f32 v101, v102, v103
	v_cvt_pk_bf16_f32 v102, v96, v97
	v_cvt_pk_bf16_f32 v103, v98, v99
	global_store_dwordx4 v[166:167], v[108:111], off
	global_store_dwordx4 v[166:167], v[100:103], off offset:256
	v_add_f32_e32 v128, v128, v129
	v_add_f32_e32 v130, v130, v131
	v_add_f32_e32 v104, v128, v130
	v_lshl_add_u64 v[194:195], v[166:167], 0, s[100:101]
	s_waitcnt vmcnt(14)
; __device__ __forceinline__ unsigned cvt_pk_bf16(float lo, float hi) { unsigned r; asm volatile("v_cvt_pk_bf16_f32 %0, %1, %2" : "=v"(r) : "v"(lo), "v"(hi)); return r; }
; __device__ __forceinline__ float bf_lo(unsigned w) { return __uint_as_float(w << 16); }
; __device__ __forceinline__ float bf_hi(unsigned w) { return __uint_as_float(w & 0xffff0000u); }
; __device__ __forceinline__ float fast_sigmoid(float x) { return __builtin_amdgcn_rcpf(1.0f + __expf(-x)); }
;     __device__ __forceinline__ void operator()(const f32x4 (&acc)[2][2][4][2], const pg8::Unit& u, int wr, int wc, int fr_, int fq_, LAS const unsigned char* xl) const {
;     ...
;                     for (int bj = 0; bj < 2; ++bj) { const size_t off = (size_t)row * DM + col + bj * 128;
;                         const u32x4 h4 = hw[mm][bj];
;                         f32x4 a = {bf_lo(h4.x), bf_hi(h4.x), bf_lo(h4.y), bf_hi(h4.y)}, b = {bf_lo(h4.z), bf_hi(h4.z), bf_lo(h4.w), bf_hi(h4.w)};
;                         f32x4 d0 = acc[ai][bj][m][0], d1 = acc[ai][bj][m][1];
;                         if (MODE == 4) { const u32x4 p4 = pw[mm][bj];
;                             d0[0] = fast_sigmoid(d0[0] * rinv) * bf_lo(p4.x); d0[1] = fast_sigmoid(d0[1] * rinv) * bf_hi(p4.x);
;                             d0[2] = fast_sigmoid(d0[2] * rinv) * bf_lo(p4.y); d0[3] = fast_sigmoid(d0[3] * rinv) * bf_hi(p4.y);
;                             d1[0] = fast_sigmoid(d1[0] * rinv) * bf_lo(p4.z); d1[1] = fast_sigmoid(d1[1] * rinv) * bf_hi(p4.z);
;                             d1[2] = fast_sigmoid(d1[2] * rinv) * bf_lo(p4.w); d1[3] = fast_sigmoid(d1[3] * rinv) * bf_hi(p4.w); }
;                         a += d0; b += d1;
;                         u32x4 w; w.x = pg8::cvt_pk_bf16(a[0], a[1]); w.y = pg8::cvt_pk_bf16(a[2], a[3]); w.z = pg8::cvt_pk_bf16(b[0], b[1]); w.w = pg8::cvt_pk_bf16(b[2], b[3]);
;                         *(u32x4*)(O + off) = w;
;                         ss += (a[0] * a[0] + a[1] * a[1]) + (a[2] * a[2] + a[3] * a[3]) + (b[0] * b[0] + b[1] * b[1]) + (b[2] * b[2] + b[3] * b[3]); }
	v_lshlrev_b32_e32 v136, 16, v144
	v_lshlrev_b32_e32 v137, 16, v145
	v_lshlrev_b32_e32 v138, 16, v146
	v_lshlrev_b32_e32 v139, 16, v147
	v_lshlrev_b32_e32 v140, 16, v148
	v_lshlrev_b32_e32 v141, 16, v149
	v_lshlrev_b32_e32 v142, 16, v150
	v_lshlrev_b32_e32 v143, 16, v151
	v_and_b32_e32 v144, 0xffff0000, v144
	v_and_b32_e32 v145, 0xffff0000, v145
	v_and_b32_e32 v146, 0xffff0000, v146
	v_and_b32_e32 v147, 0xffff0000, v147
	v_and_b32_e32 v148, 0xffff0000, v148
	v_and_b32_e32 v149, 0xffff0000, v149
	v_and_b32_e32 v150, 0xffff0000, v150
	v_and_b32_e32 v151, 0xffff0000, v151
	v_add_f32_e32 v92, v92, v136
	v_add_f32_e32 v93, v93, v144
	v_add_f32_e32 v94, v94, v137
	v_add_f32_e32 v95, v95, v145
	v_add_f32_e32 v88, v88, v138
	v_add_f32_e32 v89, v89, v146
	v_add_f32_e32 v90, v90, v139
	v_add_f32_e32 v91, v91, v147
	v_add_f32_e32 v84, v84, v140
	v_add_f32_e32 v85, v85, v148
	v_add_f32_e32 v86, v86, v141
	v_add_f32_e32 v87, v87, v149
	v_add_f32_e32 v80, v80, v142
	v_add_f32_e32 v81, v81, v150
	v_add_f32_e32 v82, v82, v143
	v_add_f32_e32 v83, v83, v151
	v_mul_f32_e32 v136, v92, v92
	v_mul_f32_e32 v137, v88, v88
	v_mul_f32_e32 v138, v84, v84
	v_mul_f32_e32 v139, v80, v80
	v_fmac_f32_e32 v136, v93, v93
	v_fmac_f32_e32 v137, v89, v89
	v_fmac_f32_e32 v138, v85, v85
	v_fmac_f32_e32 v139, v81, v81
	v_fmac_f32_e32 v136, v94, v94
	v_fmac_f32_e32 v137, v90, v90
	v_fmac_f32_e32 v138, v86, v86
	v_fmac_f32_e32 v139, v82, v82
	v_fmac_f32_e32 v136, v95, v95
	v_fmac_f32_e32 v137, v91, v91
	v_fmac_f32_e32 v138, v87, v87
	v_fmac_f32_e32 v139, v83, v83
	v_cvt_pk_bf16_f32 v92, v92, v93
	v_cvt_pk_bf16_f32 v93, v94, v95
	v_cvt_pk_bf16_f32 v94, v88, v89
	v_cvt_pk_bf16_f32 v95, v90, v91
	v_cvt_pk_bf16_f32 v84, v84, v85
	v_cvt_pk_bf16_f32 v85, v86, v87
	v_cvt_pk_bf16_f32 v86, v80, v81
	v_cvt_pk_bf16_f32 v87, v82, v83
	global_store_dwordx4 v[194:195], v[92:95], off
	global_store_dwordx4 v[194:195], v[84:87], off offset:256
	v_add_f32_e32 v136, v136, v137
	v_add_f32_e32 v138, v138, v139
	v_add_f32_e32 v88, v136, v138
	v_lshl_add_u64 v[166:167], v[194:195], 0, s[100:101]
	s_waitcnt vmcnt(14)
	v_lshlrev_b32_e32 v144, 16, v152
	v_lshlrev_b32_e32 v145, 16, v153
	v_lshlrev_b32_e32 v146, 16, v154
	v_lshlrev_b32_e32 v147, 16, v155
	v_lshlrev_b32_e32 v148, 16, v168
	v_lshlrev_b32_e32 v149, 16, v169
	v_lshlrev_b32_e32 v150, 16, v170
	v_lshlrev_b32_e32 v151, 16, v171
	v_and_b32_e32 v152, 0xffff0000, v152
	v_and_b32_e32 v153, 0xffff0000, v153
	v_and_b32_e32 v154, 0xffff0000, v154
	v_and_b32_e32 v155, 0xffff0000, v155
	v_and_b32_e32 v168, 0xffff0000, v168
	v_and_b32_e32 v169, 0xffff0000, v169
	v_and_b32_e32 v170, 0xffff0000, v170
	v_and_b32_e32 v171, 0xffff0000, v171
	v_add_f32_e32 v76, v76, v144
	v_add_f32_e32 v77, v77, v152
	v_add_f32_e32 v78, v78, v145
	v_add_f32_e32 v79, v79, v153
	v_add_f32_e32 v72, v72, v146
	v_add_f32_e32 v73, v73, v154
	v_add_f32_e32 v74, v74, v147
	v_add_f32_e32 v75, v75, v155
	v_add_f32_e32 v68, v68, v148
	v_add_f32_e32 v69, v69, v168
	v_add_f32_e32 v70, v70, v149
	v_add_f32_e32 v71, v71, v169
	v_add_f32_e32 v64, v64, v150
	v_add_f32_e32 v65, v65, v170
	v_add_f32_e32 v66, v66, v151
	v_add_f32_e32 v67, v67, v171
	v_mul_f32_e32 v144, v76, v76
	v_mul_f32_e32 v145, v72, v72
	v_mul_f32_e32 v146, v68, v68
	v_mul_f32_e32 v147, v64, v64
	v_fmac_f32_e32 v144, v77, v77
	v_fmac_f32_e32 v145, v73, v73
	v_fmac_f32_e32 v146, v69, v69
	v_fmac_f32_e32 v147, v65, v65
	v_fmac_f32_e32 v144, v78, v78
	v_fmac_f32_e32 v145, v74, v74
	v_fmac_f32_e32 v146, v70, v70
	v_fmac_f32_e32 v147, v66, v66
	v_fmac_f32_e32 v144, v79, v79
	v_fmac_f32_e32 v145, v75, v75
	v_fmac_f32_e32 v146, v71, v71
	v_fmac_f32_e32 v147, v67, v67
	v_cvt_pk_bf16_f32 v76, v76, v77
	v_cvt_pk_bf16_f32 v77, v78, v79
	v_cvt_pk_bf16_f32 v78, v72, v73
	v_cvt_pk_bf16_f32 v79, v74, v75
	v_cvt_pk_bf16_f32 v68, v68, v69
	v_cvt_pk_bf16_f32 v69, v70, v71
	v_cvt_pk_bf16_f32 v70, v64, v65
	v_cvt_pk_bf16_f32 v71, v66, v67
	global_store_dwordx4 v[166:167], v[76:79], off
	global_store_dwordx4 v[166:167], v[68:71], off offset:256
	v_add_f32_e32 v144, v144, v145
	v_add_f32_e32 v146, v146, v147
	v_add_f32_e32 v72, v144, v146
	v_lshl_add_u64 v[194:195], v[166:167], 0, s[0:1]
	s_waitcnt vmcnt(14)
	v_lshlrev_b32_e32 v152, 16, v172
	v_lshlrev_b32_e32 v153, 16, v173
	v_lshlrev_b32_e32 v154, 16, v174
	v_lshlrev_b32_e32 v155, 16, v175
	v_lshlrev_b32_e32 v168, 16, v176
	v_lshlrev_b32_e32 v169, 16, v177
	v_lshlrev_b32_e32 v170, 16, v178
	v_lshlrev_b32_e32 v171, 16, v179
	v_and_b32_e32 v172, 0xffff0000, v172
	v_and_b32_e32 v173, 0xffff0000, v173
	v_and_b32_e32 v174, 0xffff0000, v174
	v_and_b32_e32 v175, 0xffff0000, v175
	v_and_b32_e32 v176, 0xffff0000, v176
	v_and_b32_e32 v177, 0xffff0000, v177
	v_and_b32_e32 v178, 0xffff0000, v178
	v_and_b32_e32 v179, 0xffff0000, v179
	v_add_f32_e32 v60, v60, v152
	v_add_f32_e32 v61, v61, v172
	v_add_f32_e32 v62, v62, v153
	v_add_f32_e32 v63, v63, v173
	v_add_f32_e32 v56, v56, v154
	v_add_f32_e32 v57, v57, v174
	v_add_f32_e32 v58, v58, v155
	v_add_f32_e32 v59, v59, v175
	v_add_f32_e32 v52, v52, v168
	v_add_f32_e32 v53, v53, v176
	v_add_f32_e32 v54, v54, v169
	v_add_f32_e32 v55, v55, v177
	v_add_f32_e32 v48, v48, v170
	v_add_f32_e32 v49, v49, v178
	v_add_f32_e32 v50, v50, v171
	v_add_f32_e32 v51, v51, v179
	v_mul_f32_e32 v152, v60, v60
	v_mul_f32_e32 v153, v56, v56
	v_mul_f32_e32 v154, v52, v52
	v_mul_f32_e32 v155, v48, v48
	v_fmac_f32_e32 v152, v61, v61
	v_fmac_f32_e32 v153, v57, v57
	v_fmac_f32_e32 v154, v53, v53
	v_fmac_f32_e32 v155, v49, v49
	v_fmac_f32_e32 v152, v62, v62
	v_fmac_f32_e32 v153, v58, v58
	v_fmac_f32_e32 v154, v54, v54
	v_fmac_f32_e32 v155, v50, v50
	v_fmac_f32_e32 v152, v63, v63
	v_fmac_f32_e32 v153, v59, v59
	v_fmac_f32_e32 v154, v55, v55
	v_fmac_f32_e32 v155, v51, v51
	v_cvt_pk_bf16_f32 v60, v60, v61
	v_cvt_pk_bf16_f32 v61, v62, v63
	v_cvt_pk_bf16_f32 v62, v56, v57
	v_cvt_pk_bf16_f32 v63, v58, v59
	v_cvt_pk_bf16_f32 v52, v52, v53
	v_cvt_pk_bf16_f32 v53, v54, v55
	v_cvt_pk_bf16_f32 v54, v48, v49
	v_cvt_pk_bf16_f32 v55, v50, v51
	global_store_dwordx4 v[194:195], v[60:63], off
	global_store_dwordx4 v[194:195], v[52:55], off offset:256
	v_add_f32_e32 v152, v152, v153
	v_add_f32_e32 v154, v154, v155
	v_add_f32_e32 v56, v152, v154
	v_lshl_add_u64 v[166:167], v[194:195], 0, s[100:101]
	s_waitcnt vmcnt(14)
; __device__ __forceinline__ unsigned cvt_pk_bf16(float lo, float hi) { unsigned r; asm volatile("v_cvt_pk_bf16_f32 %0, %1, %2" : "=v"(r) : "v"(lo), "v"(hi)); return r; }
; __device__ __forceinline__ float bf_lo(unsigned w) { return __uint_as_float(w << 16); }
; __device__ __forceinline__ float bf_hi(unsigned w) { return __uint_as_float(w & 0xffff0000u); }
; __device__ __forceinline__ float fast_sigmoid(float x) { return __builtin_amdgcn_rcpf(1.0f + __expf(-x)); }
;     __device__ __forceinline__ void operator()(const f32x4 (&acc)[2][2][4][2], const pg8::Unit& u, int wr, int wc, int fr_, int fq_, LAS const unsigned char* xl) const {
;     ...
;                     for (int bj = 0; bj < 2; ++bj) { const size_t off = (size_t)row * DM + col + bj * 128;
;                         const u32x4 h4 = hw[mm][bj];
;                         f32x4 a = {bf_lo(h4.x), bf_hi(h4.x), bf_lo(h4.y), bf_hi(h4.y)}, b = {bf_lo(h4.z), bf_hi(h4.z), bf_lo(h4.w), bf_hi(h4.w)};
;                         f32x4 d0 = acc[ai][bj][m][0], d1 = acc[ai][bj][m][1];
;                         if (MODE == 4) { const u32x4 p4 = pw[mm][bj];
;                             d0[0] = fast_sigmoid(d0[0] * rinv) * bf_lo(p4.x); d0[1] = fast_sigmoid(d0[1] * rinv) * bf_hi(p4.x);
;                             d0[2] = fast_sigmoid(d0[2] * rinv) * bf_lo(p4.y); d0[3] = fast_sigmoid(d0[3] * rinv) * bf_hi(p4.y);
;                             d1[0] = fast_sigmoid(d1[0] * rinv) * bf_lo(p4.z); d1[1] = fast_sigmoid(d1[1] * rinv) * bf_hi(p4.z);
;                             d1[2] = fast_sigmoid(d1[2] * rinv) * bf_lo(p4.w); d1[3] = fast_sigmoid(d1[3] * rinv) * bf_hi(p4.w); }
;                         a += d0; b += d1;
;                         u32x4 w; w.x = pg8::cvt_pk_bf16(a[0], a[1]); w.y = pg8::cvt_pk_bf16(a[2], a[3]); w.z = pg8::cvt_pk_bf16(b[0], b[1]); w.w = pg8::cvt_pk_bf16(b[2], b[3]);
;                         *(u32x4*)(O + off) = w;
;                         ss += (a[0] * a[0] + a[1] * a[1]) + (a[2] * a[2] + a[3] * a[3]) + (b[0] * b[0] + b[1] * b[1]) + (b[2] * b[2] + b[3] * b[3]); }
	v_lshlrev_b32_e32 v172, 16, v180
	v_lshlrev_b32_e32 v173, 16, v181
	v_lshlrev_b32_e32 v174, 16, v182
	v_lshlrev_b32_e32 v175, 16, v183
	v_lshlrev_b32_e32 v176, 16, v188
	v_lshlrev_b32_e32 v177, 16, v189
	v_lshlrev_b32_e32 v178, 16, v190
	v_lshlrev_b32_e32 v179, 16, v191
	v_and_b32_e32 v180, 0xffff0000, v180
	v_and_b32_e32 v181, 0xffff0000, v181
	v_and_b32_e32 v182, 0xffff0000, v182
	v_and_b32_e32 v183, 0xffff0000, v183
	v_and_b32_e32 v188, 0xffff0000, v188
	v_and_b32_e32 v189, 0xffff0000, v189
	v_and_b32_e32 v190, 0xffff0000, v190
	v_and_b32_e32 v191, 0xffff0000, v191
	v_add_f32_e32 v44, v44, v172
	v_add_f32_e32 v45, v45, v180
	v_add_f32_e32 v46, v46, v173
	v_add_f32_e32 v47, v47, v181
	v_add_f32_e32 v40, v40, v174
	v_add_f32_e32 v41, v41, v182
	v_add_f32_e32 v42, v42, v175
	v_add_f32_e32 v43, v43, v183
	v_add_f32_e32 v36, v36, v176
	v_add_f32_e32 v37, v37, v188
	v_add_f32_e32 v38, v38, v177
	v_add_f32_e32 v39, v39, v189
	v_add_f32_e32 v32, v32, v178
	v_add_f32_e32 v33, v33, v190
	v_add_f32_e32 v34, v34, v179
	v_add_f32_e32 v35, v35, v191
	v_mul_f32_e32 v172, v44, v44
	v_mul_f32_e32 v173, v40, v40
	v_mul_f32_e32 v174, v36, v36
	v_mul_f32_e32 v175, v32, v32
	v_fmac_f32_e32 v172, v45, v45
	v_fmac_f32_e32 v173, v41, v41
	v_fmac_f32_e32 v174, v37, v37
	v_fmac_f32_e32 v175, v33, v33
	v_fmac_f32_e32 v172, v46, v46
	v_fmac_f32_e32 v173, v42, v42
	v_fmac_f32_e32 v174, v38, v38
	v_fmac_f32_e32 v175, v34, v34
	v_fmac_f32_e32 v172, v47, v47
	v_fmac_f32_e32 v173, v43, v43
	v_fmac_f32_e32 v174, v39, v39
	v_fmac_f32_e32 v175, v35, v35
	v_cvt_pk_bf16_f32 v44, v44, v45
	v_cvt_pk_bf16_f32 v45, v46, v47
	v_cvt_pk_bf16_f32 v46, v40, v41
	v_cvt_pk_bf16_f32 v47, v42, v43
	v_cvt_pk_bf16_f32 v36, v36, v37
	v_cvt_pk_bf16_f32 v37, v38, v39
	v_cvt_pk_bf16_f32 v38, v32, v33
	v_cvt_pk_bf16_f32 v39, v34, v35
	global_store_dwordx4 v[166:167], v[44:47], off
	global_store_dwordx4 v[166:167], v[36:39], off offset:256
	v_add_f32_e32 v172, v172, v173
	v_add_f32_e32 v174, v174, v175
	v_add_f32_e32 v40, v172, v174
	v_lshl_add_u64 v[194:195], v[166:167], 0, s[100:101]
	s_waitcnt vmcnt(14)
	v_lshlrev_b32_e32 v180, 16, v204
	v_lshlrev_b32_e32 v181, 16, v205
	v_lshlrev_b32_e32 v182, 16, v206
	v_lshlrev_b32_e32 v183, 16, v207
	v_lshlrev_b32_e32 v188, 16, v208
	v_lshlrev_b32_e32 v189, 16, v209
	v_lshlrev_b32_e32 v190, 16, v210
	v_lshlrev_b32_e32 v191, 16, v211
	v_and_b32_e32 v204, 0xffff0000, v204
	v_and_b32_e32 v205, 0xffff0000, v205
	v_and_b32_e32 v206, 0xffff0000, v206
	v_and_b32_e32 v207, 0xffff0000, v207
	v_and_b32_e32 v208, 0xffff0000, v208
	v_and_b32_e32 v209, 0xffff0000, v209
	v_and_b32_e32 v210, 0xffff0000, v210
	v_and_b32_e32 v211, 0xffff0000, v211
	v_add_f32_e32 v28, v28, v180
	v_add_f32_e32 v29, v29, v204
	v_add_f32_e32 v30, v30, v181
	v_add_f32_e32 v31, v31, v205
	v_add_f32_e32 v24, v24, v182
	v_add_f32_e32 v25, v25, v206
	v_add_f32_e32 v26, v26, v183
	v_add_f32_e32 v27, v27, v207
	v_add_f32_e32 v20, v20, v188
	v_add_f32_e32 v21, v21, v208
	v_add_f32_e32 v22, v22, v189
	v_add_f32_e32 v23, v23, v209
	v_add_f32_e32 v16, v16, v190
	v_add_f32_e32 v17, v17, v210
	v_add_f32_e32 v18, v18, v191
	v_add_f32_e32 v19, v19, v211
	v_mul_f32_e32 v180, v28, v28
	v_mul_f32_e32 v181, v24, v24
	v_mul_f32_e32 v182, v20, v20
	v_mul_f32_e32 v183, v16, v16
	v_fmac_f32_e32 v180, v29, v29
	v_fmac_f32_e32 v181, v25, v25
	v_fmac_f32_e32 v182, v21, v21
	v_fmac_f32_e32 v183, v17, v17
	v_fmac_f32_e32 v180, v30, v30
	v_fmac_f32_e32 v181, v26, v26
	v_fmac_f32_e32 v182, v22, v22
	v_fmac_f32_e32 v183, v18, v18
	v_fmac_f32_e32 v180, v31, v31
	v_fmac_f32_e32 v181, v27, v27
	v_fmac_f32_e32 v182, v23, v23
	v_fmac_f32_e32 v183, v19, v19
	v_cvt_pk_bf16_f32 v28, v28, v29
	v_cvt_pk_bf16_f32 v29, v30, v31
	v_cvt_pk_bf16_f32 v30, v24, v25
	v_cvt_pk_bf16_f32 v31, v26, v27
	v_cvt_pk_bf16_f32 v20, v20, v21
	v_cvt_pk_bf16_f32 v21, v22, v23
	v_cvt_pk_bf16_f32 v22, v16, v17
	v_cvt_pk_bf16_f32 v23, v18, v19
	global_store_dwordx4 v[194:195], v[28:31], off
	global_store_dwordx4 v[194:195], v[20:23], off offset:256
	v_add_f32_e32 v180, v180, v181
	v_add_f32_e32 v182, v182, v183
	v_add_f32_e32 v24, v180, v182
	v_lshl_add_u64 v[166:167], v[194:195], 0, s[100:101]
	s_waitcnt vmcnt(12)
; __device__ __forceinline__ unsigned cvt_pk_bf16(float lo, float hi) { unsigned r; asm volatile("v_cvt_pk_bf16_f32 %0, %1, %2" : "=v"(r) : "v"(lo), "v"(hi)); return r; }
; __device__ __forceinline__ float bf_lo(unsigned w) { return __uint_as_float(w << 16); }
; __device__ __forceinline__ float bf_hi(unsigned w) { return __uint_as_float(w & 0xffff0000u); }
; __device__ __forceinline__ float fast_sigmoid(float x) { return __builtin_amdgcn_rcpf(1.0f + __expf(-x)); }
;     __device__ __forceinline__ void operator()(const f32x4 (&acc)[2][2][4][2], const pg8::Unit& u, int wr, int wc, int fr_, int fq_, LAS const unsigned char* xl) const {
;     ...
;                     for (int bj = 0; bj < 2; ++bj) { const size_t off = (size_t)row * DM + col + bj * 128;
;                         const u32x4 h4 = hw[mm][bj];
;                         f32x4 a = {bf_lo(h4.x), bf_hi(h4.x), bf_lo(h4.y), bf_hi(h4.y)}, b = {bf_lo(h4.z), bf_hi(h4.z), bf_lo(h4.w), bf_hi(h4.w)};
;                         f32x4 d0 = acc[ai][bj][m][0], d1 = acc[ai][bj][m][1];
;                         if (MODE == 4) { const u32x4 p4 = pw[mm][bj];
;                             d0[0] = fast_sigmoid(d0[0] * rinv) * bf_lo(p4.x); d0[1] = fast_sigmoid(d0[1] * rinv) * bf_hi(p4.x);
;                             d0[2] = fast_sigmoid(d0[2] * rinv) * bf_lo(p4.y); d0[3] = fast_sigmoid(d0[3] * rinv) * bf_hi(p4.y);
;                             d1[0] = fast_sigmoid(d1[0] * rinv) * bf_lo(p4.z); d1[1] = fast_sigmoid(d1[1] * rinv) * bf_hi(p4.z);
;                             d1[2] = fast_sigmoid(d1[2] * rinv) * bf_lo(p4.w); d1[3] = fast_sigmoid(d1[3] * rinv) * bf_hi(p4.w); }
;                         a += d0; b += d1;
;                         u32x4 w; w.x = pg8::cvt_pk_bf16(a[0], a[1]); w.y = pg8::cvt_pk_bf16(a[2], a[3]); w.z = pg8::cvt_pk_bf16(b[0], b[1]); w.w = pg8::cvt_pk_bf16(b[2], b[3]);
;                         *(u32x4*)(O + off) = w;
;                         ss += (a[0] * a[0] + a[1] * a[1]) + (a[2] * a[2] + a[3] * a[3]) + (b[0] * b[0] + b[1] * b[1]) + (b[2] * b[2] + b[3] * b[3]); }
;                     ss = xrow16_sum(ss);
;                     if (fq == 0) part_out[(size_t)row * 16 + u.pn * 4 + wc] = ss;
;                 }
	v_lshlrev_b32_e32 v204, 16, v212
	v_lshlrev_b32_e32 v205, 16, v213
	v_lshlrev_b32_e32 v206, 16, v214
	v_lshlrev_b32_e32 v207, 16, v215
	v_lshlrev_b32_e32 v208, 16, v216
	v_lshlrev_b32_e32 v209, 16, v217
	v_lshlrev_b32_e32 v210, 16, v218
	v_lshlrev_b32_e32 v211, 16, v219
	v_and_b32_e32 v212, 0xffff0000, v212
	v_and_b32_e32 v213, 0xffff0000, v213
	v_and_b32_e32 v214, 0xffff0000, v214
	v_and_b32_e32 v215, 0xffff0000, v215
	v_and_b32_e32 v216, 0xffff0000, v216
	v_and_b32_e32 v217, 0xffff0000, v217
	v_and_b32_e32 v218, 0xffff0000, v218
	v_and_b32_e32 v219, 0xffff0000, v219
	v_add_f32_e32 v12, v12, v204
	v_add_f32_e32 v13, v13, v212
	v_add_f32_e32 v14, v14, v205
	v_add_f32_e32 v15, v15, v213
	v_add_f32_e32 v8, v8, v206
	v_add_f32_e32 v9, v9, v214
	v_add_f32_e32 v10, v10, v207
	v_add_f32_e32 v11, v11, v215
	v_add_f32_e32 v4, v4, v208
	v_add_f32_e32 v5, v5, v216
	v_add_f32_e32 v6, v6, v209
	v_add_f32_e32 v7, v7, v217
	v_add_f32_e32 v0, v0, v210
	v_add_f32_e32 v1, v1, v218
	v_add_f32_e32 v2, v2, v211
	v_add_f32_e32 v3, v3, v219
	v_mul_f32_e32 v204, v12, v12
	v_mul_f32_e32 v205, v8, v8
	v_mul_f32_e32 v206, v4, v4
	v_mul_f32_e32 v207, v0, v0
	v_fmac_f32_e32 v204, v13, v13
	v_fmac_f32_e32 v205, v9, v9
	v_fmac_f32_e32 v206, v5, v5
	v_fmac_f32_e32 v207, v1, v1
	v_fmac_f32_e32 v204, v14, v14
	v_fmac_f32_e32 v205, v10, v10
	v_fmac_f32_e32 v206, v6, v6
	v_fmac_f32_e32 v207, v2, v2
	v_fmac_f32_e32 v204, v15, v15
	v_fmac_f32_e32 v205, v11, v11
	v_fmac_f32_e32 v206, v7, v7
	v_fmac_f32_e32 v207, v3, v3
	v_cvt_pk_bf16_f32 v12, v12, v13
	v_cvt_pk_bf16_f32 v13, v14, v15
	v_cvt_pk_bf16_f32 v14, v8, v9
	v_cvt_pk_bf16_f32 v15, v10, v11
	v_cvt_pk_bf16_f32 v4, v4, v5
	v_cvt_pk_bf16_f32 v5, v6, v7
	v_cvt_pk_bf16_f32 v6, v0, v1
	v_cvt_pk_bf16_f32 v7, v2, v3
	global_store_dwordx4 v[166:167], v[12:15], off
	global_store_dwordx4 v[166:167], v[4:7], off offset:256
	v_add_f32_e32 v204, v204, v205
	v_add_f32_e32 v206, v206, v207
	v_add_f32_e32 v8, v204, v206
	v_mov_b32_e32 v125, v124
	v_mov_b32_e32 v105, v104
	v_mov_b32_e32 v89, v88
	v_mov_b32_e32 v73, v72
	v_mov_b32_e32 v57, v56
	v_mov_b32_e32 v41, v40
	v_mov_b32_e32 v25, v24
	v_mov_b32_e32 v9, v8
	v_permlane16_swap_b32_e32 v124, v125
	v_permlane16_swap_b32_e32 v104, v105
	v_permlane16_swap_b32_e32 v88, v89
	v_permlane16_swap_b32_e32 v72, v73
	v_permlane16_swap_b32_e32 v56, v57
	v_permlane16_swap_b32_e32 v40, v41
	v_permlane16_swap_b32_e32 v24, v25
	v_permlane16_swap_b32_e32 v8, v9
	v_add_f32_e32 v124, v124, v125
	v_add_f32_e32 v104, v104, v105
	v_add_f32_e32 v88, v88, v89
	v_add_f32_e32 v72, v72, v73
	v_add_f32_e32 v56, v56, v57
	v_add_f32_e32 v40, v40, v41
	v_add_f32_e32 v24, v24, v25
	v_add_f32_e32 v8, v8, v9
	v_mov_b32_e32 v125, v124
	v_mov_b32_e32 v105, v104
	v_mov_b32_e32 v89, v88
	v_mov_b32_e32 v73, v72
	v_mov_b32_e32 v57, v56
	v_mov_b32_e32 v41, v40
	v_mov_b32_e32 v25, v24
	v_mov_b32_e32 v9, v8
	v_permlane32_swap_b32_e32 v124, v125
	v_permlane32_swap_b32_e32 v104, v105
	v_permlane32_swap_b32_e32 v88, v89
	v_permlane32_swap_b32_e32 v72, v73
	v_permlane32_swap_b32_e32 v56, v57
	v_permlane32_swap_b32_e32 v40, v41
	v_permlane32_swap_b32_e32 v24, v25
	v_permlane32_swap_b32_e32 v8, v9
	v_add_f32_e32 v124, v124, v125
	v_add_f32_e32 v104, v104, v105
	v_add_f32_e32 v88, v88, v89
	v_add_f32_e32 v72, v72, v73
	v_add_f32_e32 v56, v56, v57
	v_add_f32_e32 v40, v40, v41
	v_add_f32_e32 v24, v24, v25
	v_add_f32_e32 v8, v8, v9
	s_mov_b32 s100, 0x2000
	v_cmp_eq_u32_e32 vcc, 0, v185
	v_lshl_add_u64 v[202:203], v[200:201], 0, s[100:101]
	s_and_saveexec_b64 s[26:27], vcc
	global_store_dword v[200:201], v124, off
	global_store_dword v[200:201], v104, off offset:1024
	global_store_dword v[200:201], v88, off offset:2048
	global_store_dword v[200:201], v72, off offset:3072
	global_store_dword v[202:203], v56, off
	global_store_dword v[202:203], v40, off offset:1024
	global_store_dword v[202:203], v24, off offset:2048
	global_store_dword v[202:203], v8, off offset:3072
	s_or_b64 exec, exec, s[26:27]
	s_and_b64 vcc, exec, s[6:7]
	s_mov_b64 s[0:1], -1
	s_cbranch_vccnz .LBB0_484
	s_andn2_b64 vcc, exec, s[18:19]
	s_cbranch_vccnz .LBB0_483
	s_barrier
	s_branch .LBB0_483

; #define LAS __attribute__((address_space(3)))
; __device__ __forceinline__ float bf_lo(unsigned w) { return __uint_as_float(w << 16); }
;     __device__ __forceinline__ void operator()(const f32x4 (&acc)[2][2][4][2], const pg8::Unit& u, int wr, int wc, int fr_, int fq_, LAS const unsigned char* xl) const {
;     ...
;                 for (int m = 0; m < 4; ++m) { const f32x4 pv = *(LAS const f32x4*)(xl + (ai * 128 + wr * 64 + m * 16 + fr) * 64 + fq * 16); rv[ai][m] = (pv[0] + pv[1]) + (pv[2] + pv[3]); }
; #pragma unroll
;             for (int ai = 0; ai < 2; ++ai)
; #pragma unroll
;                 for (int m = 0; m < 4; ++m) rv[ai][m] = __builtin_amdgcn_rsqf(xrow16_sum(rv[ai][m]) * (1.0f / 1024.0f) + EPS);
;     ...
;                 u32x4 hw[MB][2], pw[MB][2];
; #pragma unroll
;                 for (int m = 0; m < MB; ++m)
; #pragma unroll
;                     for (int bj = 0; bj < 2; ++bj) { const size_t off = (size_t)(row0 + ai * 128 + (mb + m) * 16) * DM + col + bj * 128;
;                         hw[m][bj] = *(const u32x4*)(h_old + off); if (MODE == 4) pw[m][bj] = *(const u32x4*)(pp + off); }
; #pragma unroll
;                 for (int mm = 0; mm < MB; ++mm) {
;                     const int m = mb + mm;
;                     const int row = row0 + ai * 128 + m * 16; const float rinv = rv[ai][m];
;                     float ss = 0.f;
; #pragma unroll
;                     for (int bj = 0; bj < 2; ++bj) { const size_t off = (size_t)row * DM + col + bj * 128;
;                         const u32x4 h4 = hw[mm][bj];
;                         f32x4 a = {bf_lo(h4.x), bf_hi(h4.x), bf_lo(h4.y), bf_hi(h4.y)}, b = {bf_lo(h4.z), bf_hi(h4.z), bf_lo(h4.w), bf_hi(h4.w)};
;                         f32x4 d0 = acc[ai][bj][m][0], d1 = acc[ai][bj][m][1];
;                         if (MODE == 4) { const u32x4 p4 = pw[mm][bj];
;                             d0[0] = fast_sigmoid(d0[0] * rinv) * bf_lo(p4.x); d0[1] = fast_sigmoid(d0[1] * rinv) * bf_hi(p4.x);
;                             d0[2] = fast_sigmoid(d0[2] * rinv) * bf_lo(p4.y); d0[3] = fast_sigmoid(d0[3] * rinv) * bf_hi(p4.y);
;                             d1[0] = fast_sigmoid(d1[0] * rinv) * bf_lo(p4.z); d1[1] = fast_sigmoid(d1[1] * rinv) * bf_hi(p4.z);
;                             d1[2] = fast_sigmoid(d1[2] * rinv) * bf_lo(p4.w); d1[3] = fast_sigmoid(d1[3] * rinv) * bf_hi(p4.w); }
.LBB0_573:
	v_mov_b32_e32 v128, v237
	v_mov_b32_e32 v136, v238
	s_add_i32 s1, 0, 0x20000
	v_add_u32_e32 v137, s51, v128
	v_lshlrev_b32_e32 v128, 4, v136
	v_lshlrev_b32_e32 v129, 6, v137
	v_add3_u32 v138, s1, v128, v129
	ds_read_b128 v[128:131], v138
	ds_read_b128 v[132:135], v138 offset:1024
	v_lshl_add_u32 v146, s0, 8, v137
	s_lshl_b32 s0, s2, 8
	s_or_b32 s0, s0, s52
	s_waitcnt lgkmcnt(0)
	v_add_f32_e32 v128, v128, v129
	v_add_f32_e32 v129, v130, v131
	v_add_f32_e32 v139, v128, v129
	ds_read_b128 v[128:131], v138 offset:2048
	v_add_f32_e32 v132, v132, v133
	v_add_f32_e32 v133, v134, v135
	v_add_f32_e32 v140, v132, v133
	ds_read_b128 v[132:135], v138 offset:3072
	s_waitcnt lgkmcnt(0)
	v_add_f32_e32 v128, v128, v129
	v_add_f32_e32 v129, v130, v131
	v_add_f32_e32 v141, v128, v129
	ds_read_b128 v[128:131], v138 offset:8192
	v_add_f32_e32 v132, v132, v133
	v_add_f32_e32 v133, v134, v135
	v_add_f32_e32 v142, v132, v133
	ds_read_b128 v[132:135], v138 offset:9216
	s_waitcnt lgkmcnt(0)
	v_add_f32_e32 v128, v128, v129
	v_add_f32_e32 v129, v130, v131
	v_add_f32_e32 v143, v128, v129
	ds_read_b128 v[128:131], v138 offset:10240
	v_add_f32_e32 v144, v132, v133
	v_add_f32_e32 v145, v134, v135
	ds_read_b128 v[132:135], v138 offset:11264
	v_add_f32_e32 v138, v144, v145
	s_waitcnt lgkmcnt(0)
	v_add_f32_e32 v128, v128, v129
	v_add_f32_e32 v129, v130, v131
	v_lshl_add_u32 v144, v136, 3, s0
	v_ashrrev_i32_e32 v147, 31, v146
	v_add_f32_e32 v148, v128, v129
	v_add_f32_e32 v132, v132, v133
	v_add_f32_e32 v133, v134, v135
	v_ashrrev_i32_e32 v145, 31, v144
	v_lshlrev_b64 v[128:129], 10, v[146:147]
	v_lshl_add_u64 v[128:129], v[128:129], 0, v[144:145]
	v_readlane_b32 s28, v255, 24
	v_add_f32_e32 v132, v132, v133
	v_mov_b32_e32 v133, v139
	v_lshlrev_b64 v[128:129], 1, v[128:129]
	v_readlane_b32 s29, v255, 25
	v_permlane16_swap_b32_e32 v139, v133
	s_nop 0
	v_lshl_add_u64 v[130:131], s[28:29], 0, v[128:129]
	v_add_f32_e32 v133, v139, v133
	v_lshl_add_u64 v[128:129], s[74:75], 0, v[128:129]
	global_load_dwordx4 v[164:167], v[130:131], off nt
	v_mov_b32_e32 v134, v133
	global_load_dwordx4 v[168:171], v[128:129], off nt
	s_nop 0
	v_permlane32_swap_b32_e32 v133, v134
	v_add_f32_e32 v133, v133, v134
	v_fmamk_f32 v133, v133, 0x3a800000, v233
	v_rsq_f32_e32 v190, v133
	v_mov_b32_e32 v133, v140
	s_nop 1
	v_permlane16_swap_b32_e32 v140, v133
	v_add_f32_e32 v162, v140, v133
	v_mov_b32_e32 v133, v141
	s_nop 1
	v_permlane16_swap_b32_e32 v141, v133
	v_add_f32_e32 v160, v141, v133
	v_mov_b32_e32 v133, v142
	s_nop 1
	v_permlane16_swap_b32_e32 v142, v133
	global_load_dwordx4 v[172:175], v[130:131], off offset:256 nt
	global_load_dwordx4 v[176:179], v[128:129], off offset:256 nt
	v_add_f32_e32 v158, v142, v133
	v_mov_b32_e32 v133, v143
	s_nop 1
	v_permlane16_swap_b32_e32 v143, v133
	v_add_f32_e32 v156, v143, v133
	v_mov_b32_e32 v133, v138
	s_nop 1
	v_permlane16_swap_b32_e32 v138, v133
	v_add_f32_e32 v154, v138, v133
	v_mov_b32_e32 v133, v148
	s_nop 1
	v_permlane16_swap_b32_e32 v148, v133
	v_add_f32_e32 v152, v148, v133
	v_add_u32_e32 v148, 16, v146
	v_ashrrev_i32_e32 v149, 31, v148
	v_lshlrev_b64 v[128:129], 10, v[148:149]
	v_lshl_add_u64 v[128:129], v[128:129], 0, v[144:145]
	v_mov_b32_e32 v133, v132
	v_lshlrev_b64 v[128:129], 1, v[128:129]
	s_nop 0
	v_permlane16_swap_b32_e32 v132, v133
	v_lshl_add_u64 v[130:131], s[28:29], 0, v[128:129]
	v_lshl_add_u64 v[128:129], s[74:75], 0, v[128:129]
	v_add_f32_e32 v150, v132, v133
	v_cmp_eq_u32_e32 vcc, 0, v136
	global_load_dwordx4 v[140:143], v[130:131], off nt
	global_load_dwordx4 v[132:135], v[130:131], off offset:256 nt
	global_load_dwordx4 v[136:139], v[128:129], off nt
	s_nop 0
	global_load_dwordx4 v[128:131], v[128:129], off offset:256 nt
	v_mul_f32_e32 v126, v126, v190
	v_mul_f32_e32 v127, v127, v190
	v_mul_f32_e32 v124, v124, v190
	v_mul_f32_e32 v125, v125, v190
	v_mul_f32_e32 v126, 0xbfb8aa3b, v126
	v_mul_f32_e32 v127, 0xbfb8aa3b, v127
	v_mul_f32_e32 v120, v120, v190
	v_mul_f32_e32 v121, v121, v190
	v_mul_f32_e32 v122, v122, v190
	v_mul_f32_e32 v123, v123, v190
	v_mul_f32_e32 v124, 0xbfb8aa3b, v124
	v_mul_f32_e32 v125, 0xbfb8aa3b, v125
	v_exp_f32_e32 v126, v126
	v_exp_f32_e32 v127, v127
	v_mul_f32_e32 v120, 0xbfb8aa3b, v120
	v_mul_f32_e32 v121, 0xbfb8aa3b, v121
	v_mul_f32_e32 v122, 0xbfb8aa3b, v122
	v_mul_f32_e32 v123, 0xbfb8aa3b, v123
	v_exp_f32_e32 v124, v124
	v_exp_f32_e32 v125, v125
	v_exp_f32_e32 v120, v120
	v_exp_f32_e32 v121, v121
	v_exp_f32_e32 v122, v122
	v_exp_f32_e32 v123, v123
	v_add_f32_e32 v126, 1.0, v126
	v_add_f32_e32 v127, 1.0, v127
	v_add_f32_e32 v124, 1.0, v124
	v_add_f32_e32 v125, 1.0, v125
	v_rcp_f32_e32 v126, v126
	v_rcp_f32_e32 v127, v127
	v_add_f32_e32 v120, 1.0, v120
	v_add_f32_e32 v121, 1.0, v121
	v_add_f32_e32 v122, 1.0, v122
	v_add_f32_e32 v123, 1.0, v123
	v_rcp_f32_e32 v124, v124
	v_rcp_f32_e32 v125, v125
	v_rcp_f32_e32 v120, v120
	v_rcp_f32_e32 v121, v121
	v_rcp_f32_e32 v122, v122
	v_rcp_f32_e32 v123, v123
	v_mul_f32_e32 v116, v116, v190
	v_mul_f32_e32 v117, v117, v190
	v_mul_f32_e32 v118, v118, v190
	v_mul_f32_e32 v119, v119, v190
	v_mul_f32_e32 v112, v112, v190
	v_mul_f32_e32 v113, v113, v190
	v_lshlrev_b64 v[180:181], 11, v[146:147]
	s_waitcnt vmcnt(0)
; __device__ __forceinline__ unsigned cvt_pk_bf16(float lo, float hi) { unsigned r; asm volatile("v_cvt_pk_bf16_f32 %0, %1, %2" : "=v"(r) : "v"(lo), "v"(hi)); return r; }
; __device__ __forceinline__ float bf_lo(unsigned w) { return __uint_as_float(w << 16); }
; __device__ __forceinline__ float bf_hi(unsigned w) { return __uint_as_float(w & 0xffff0000u); }
; __device__ __forceinline__ float fast_sigmoid(float x) { return __builtin_amdgcn_rcpf(1.0f + __expf(-x)); }
;     __device__ __forceinline__ void operator()(const f32x4 (&acc)[2][2][4][2], const pg8::Unit& u, int wr, int wc, int fr_, int fq_, LAS const unsigned char* xl) const {
;     ...
;                     for (int bj = 0; bj < 2; ++bj) { const size_t off = (size_t)row * DM + col + bj * 128;
;                         const u32x4 h4 = hw[mm][bj];
;                         f32x4 a = {bf_lo(h4.x), bf_hi(h4.x), bf_lo(h4.y), bf_hi(h4.y)}, b = {bf_lo(h4.z), bf_hi(h4.z), bf_lo(h4.w), bf_hi(h4.w)};
;                         f32x4 d0 = acc[ai][bj][m][0], d1 = acc[ai][bj][m][1];
;                         if (MODE == 4) { const u32x4 p4 = pw[mm][bj];
;                             d0[0] = fast_sigmoid(d0[0] * rinv) * bf_lo(p4.x); d0[1] = fast_sigmoid(d0[1] * rinv) * bf_hi(p4.x);
;                             d0[2] = fast_sigmoid(d0[2] * rinv) * bf_lo(p4.y); d0[3] = fast_sigmoid(d0[3] * rinv) * bf_hi(p4.y);
;                             d1[0] = fast_sigmoid(d1[0] * rinv) * bf_lo(p4.z); d1[1] = fast_sigmoid(d1[1] * rinv) * bf_hi(p4.z);
;                             d1[2] = fast_sigmoid(d1[2] * rinv) * bf_lo(p4.w); d1[3] = fast_sigmoid(d1[3] * rinv) * bf_hi(p4.w); }
;                         a += d0; b += d1;
;                         u32x4 w; w.x = pg8::cvt_pk_bf16(a[0], a[1]); w.y = pg8::cvt_pk_bf16(a[2], a[3]); w.z = pg8::cvt_pk_bf16(b[0], b[1]); w.w = pg8::cvt_pk_bf16(b[2], b[3]);
;                         *(u32x4*)(O + off) = w;
;                         ss += (a[0] * a[0] + a[1] * a[1]) + (a[2] * a[2] + a[3] * a[3]) + (b[0] * b[0] + b[1] * b[1]) + (b[2] * b[2] + b[3] * b[3]); }
;                     ss = xrow16_sum(ss);
;                     if (fq == 0) part_out[(size_t)row * 16 + u.pn * 4 + wc] = ss;
	v_lshlrev_b32_e32 v182, 16, v164
	v_and_b32_e32 v183, 0xffff0000, v164
	v_lshlrev_b32_e32 v164, 16, v165
	v_and_b32_e32 v165, 0xffff0000, v165
	v_lshlrev_b32_e32 v186, 16, v168
	v_and_b32_e32 v187, 0xffff0000, v168
	v_lshlrev_b32_e32 v168, 16, v169
	v_and_b32_e32 v169, 0xffff0000, v169
	v_mul_f32_e32 v116, 0xbfb8aa3b, v116
	v_mul_f32_e32 v117, 0xbfb8aa3b, v117
	v_mul_f32_e32 v118, 0xbfb8aa3b, v118
	v_mul_f32_e32 v119, 0xbfb8aa3b, v119
	v_mul_f32_e32 v112, 0xbfb8aa3b, v112
	v_mul_f32_e32 v113, 0xbfb8aa3b, v113
	v_mul_f32_e32 v114, v114, v190
	v_mul_f32_e32 v115, v115, v190
	v_lshlrev_b32_e32 v184, 16, v166
	v_and_b32_e32 v185, 0xffff0000, v166
	v_lshlrev_b32_e32 v166, 16, v167
	v_and_b32_e32 v167, 0xffff0000, v167
	v_lshlrev_b32_e32 v188, 16, v170
	v_and_b32_e32 v189, 0xffff0000, v170
	v_lshlrev_b32_e32 v170, 16, v171
	v_and_b32_e32 v171, 0xffff0000, v171
	v_pk_fma_f32 v[126:127], v[126:127], v[168:169], v[164:165]
	v_lshl_add_u64 v[168:169], s[20:21], 0, v[180:181]
	v_exp_f32_e32 v116, v116
	v_exp_f32_e32 v117, v117
	v_exp_f32_e32 v118, v118
	v_exp_f32_e32 v119, v119
	v_exp_f32_e32 v112, v112
	v_exp_f32_e32 v113, v113
	v_mul_f32_e32 v114, 0xbfb8aa3b, v114
	v_mul_f32_e32 v115, 0xbfb8aa3b, v115
	v_pk_fma_f32 v[124:125], v[124:125], v[186:187], v[182:183]
	v_pk_fma_f32 v[164:165], v[122:123], v[170:171], v[166:167]
	v_pk_fma_f32 v[166:167], v[120:121], v[188:189], v[184:185]
	v_cvt_pk_bf16_f32 v120, v124, v125
	v_cvt_pk_bf16_f32 v121, v126, v127
	v_lshl_add_u64 v[168:169], v[144:145], 1, v[168:169]
	v_exp_f32_e32 v114, v114
	v_exp_f32_e32 v115, v115
	v_cvt_pk_bf16_f32 v122, v166, v167
	v_cvt_pk_bf16_f32 v123, v164, v165
	global_store_dwordx4 v[168:169], v[120:123], off
	v_add_f32_e32 v116, 1.0, v116
	v_add_f32_e32 v117, 1.0, v117
	v_mul_f32_e32 v120, v125, v125
	v_mul_f32_e32 v121, v127, v127
	v_fmac_f32_e32 v120, v124, v124
	v_fmac_f32_e32 v121, v126, v126
	v_add_f32_e32 v120, v120, v121
	v_mul_f32_e32 v121, v167, v167
	v_add_f32_e32 v118, 1.0, v118
	v_add_f32_e32 v119, 1.0, v119
	v_add_f32_e32 v112, 1.0, v112
	v_add_f32_e32 v113, 1.0, v113
	v_fmac_f32_e32 v121, v166, v166
	v_rcp_f32_e32 v116, v116
	v_rcp_f32_e32 v117, v117
	v_rcp_f32_e32 v118, v118
	v_rcp_f32_e32 v119, v119
	v_rcp_f32_e32 v112, v112
	v_rcp_f32_e32 v113, v113
	v_add_f32_e32 v114, 1.0, v114
	v_add_f32_e32 v115, 1.0, v115
	v_add_f32_e32 v120, v121, v120
	v_mul_f32_e32 v121, v165, v165
	v_rcp_f32_e32 v114, v114
	v_rcp_f32_e32 v115, v115
	v_fmac_f32_e32 v121, v164, v164
	v_add_f32_e32 v180, v121, v120
	v_lshlrev_b32_e32 v120, 16, v172
	v_and_b32_e32 v121, 0xffff0000, v172
	v_lshlrev_b32_e32 v122, 16, v173
	v_and_b32_e32 v123, 0xffff0000, v173
	v_lshlrev_b32_e32 v124, 16, v174
	v_and_b32_e32 v125, 0xffff0000, v174
	v_lshlrev_b32_e32 v164, 16, v176
	v_and_b32_e32 v165, 0xffff0000, v176
	v_lshlrev_b32_e32 v166, 16, v177
	v_and_b32_e32 v167, 0xffff0000, v177
	v_lshlrev_b32_e32 v170, 16, v178
	v_and_b32_e32 v171, 0xffff0000, v178
	v_lshlrev_b32_e32 v126, 16, v175
	v_and_b32_e32 v127, 0xffff0000, v175
	v_lshlrev_b32_e32 v172, 16, v179
	v_and_b32_e32 v173, 0xffff0000, v179
	v_pk_fma_f32 v[118:119], v[118:119], v[166:167], v[122:123]
	v_pk_fma_f32 v[116:117], v[116:117], v[164:165], v[120:121]
	v_pk_fma_f32 v[122:123], v[112:113], v[170:171], v[124:125]
	v_cvt_pk_bf16_f32 v112, v116, v117
	v_cvt_pk_bf16_f32 v113, v118, v119
	v_pk_fma_f32 v[120:121], v[114:115], v[172:173], v[126:127]
	v_cvt_pk_bf16_f32 v114, v122, v123
	v_mov_b32_e32 v163, v162
	v_cvt_pk_bf16_f32 v115, v120, v121
	global_store_dwordx4 v[168:169], v[112:115], off offset:256
	v_mov_b32_e32 v161, v160
	v_mov_b32_e32 v159, v158
	v_mul_f32_e32 v112, v117, v117
	v_mul_f32_e32 v113, v119, v119
	v_fmac_f32_e32 v112, v116, v116
	v_fmac_f32_e32 v113, v118, v118
	v_add_f32_e32 v112, v112, v113
	v_mul_f32_e32 v113, v123, v123
	v_fmac_f32_e32 v113, v122, v122
	v_add_f32_e32 v112, v113, v112
	v_mul_f32_e32 v113, v121, v121
	v_fmac_f32_e32 v113, v120, v120
	v_add_f32_e32 v112, v113, v112
	v_add_f32_e32 v112, v180, v112
	v_mov_b32_e32 v113, v112
	s_nop 1
	v_permlane16_swap_b32_e32 v112, v113
	v_add_f32_e32 v112, v112, v113
	v_mov_b32_e32 v157, v156
	v_mov_b32_e32 v155, v154
	v_mov_b32_e32 v153, v152
	v_mov_b32_e32 v151, v150
	s_lshl_b32 s0, s2, 2
	v_mov_b32_e32 v113, v112
	v_permlane32_swap_b32_e32 v162, v163
	v_permlane32_swap_b32_e32 v160, v161
	v_permlane32_swap_b32_e32 v158, v159
	v_permlane32_swap_b32_e32 v156, v157
	v_permlane32_swap_b32_e32 v154, v155
	v_permlane32_swap_b32_e32 v152, v153
	v_permlane32_swap_b32_e32 v150, v151
	s_ashr_i32 s1, s0, 31
	v_permlane32_swap_b32_e32 v112, v113
	s_and_saveexec_b64 s[28:29], vcc
	s_cbranch_execz .LBB0_575
	v_lshlrev_b64 v[114:115], 6, v[146:147]
	v_lshl_add_u64 v[114:115], s[18:19], 0, v[114:115]
	v_lshl_add_u64 v[114:115], s[0:1], 2, v[114:115]
	s_lshl_b32 s86, s49, 2
	v_lshl_add_u64 v[114:115], v[114:115], 0, s[86:87]
	v_add_f32_e32 v112, v112, v113
	flat_store_dword v[114:115], v112

;     __device__ __forceinline__ void operator()(const f32x4 (&acc)[2][2][4][2], const pg8::Unit& u, int wr, int wc, int fr_, int fq_, LAS const unsigned char* xl) const {
;     ...
;                 u32x4 hw[MB][2], pw[MB][2];
; #pragma unroll
;                 for (int m = 0; m < MB; ++m)
; #pragma unroll
;                     for (int bj = 0; bj < 2; ++bj) { const size_t off = (size_t)(row0 + ai * 128 + (mb + m) * 16) * DM + col + bj * 128;
;                         hw[m][bj] = *(const u32x4*)(h_old + off); if (MODE == 4) pw[m][bj] = *(const u32x4*)(pp + off); }
; #pragma unroll
;                 for (int mm = 0; mm < MB; ++mm) {
;                     const int m = mb + mm;
;                     const int row = row0 + ai * 128 + m * 16; const float rinv = rv[ai][m];
;                     float ss = 0.f;
; #pragma unroll
;                     for (int bj = 0; bj < 2; ++bj) { const size_t off = (size_t)row * DM + col + bj * 128;
;                         const u32x4 h4 = hw[mm][bj];
;                         f32x4 a = {bf_lo(h4.x), bf_hi(h4.x), bf_lo(h4.y), bf_hi(h4.y)}, b = {bf_lo(h4.z), bf_hi(h4.z), bf_lo(h4.w), bf_hi(h4.w)};
;                         f32x4 d0 = acc[ai][bj][m][0], d1 = acc[ai][bj][m][1];
;                         if (MODE == 4) { const u32x4 p4 = pw[mm][bj];
;                             d0[0] = fast_sigmoid(d0[0] * rinv) * bf_lo(p4.x); d0[1] = fast_sigmoid(d0[1] * rinv) * bf_hi(p4.x);
;                             d0[2] = fast_sigmoid(d0[2] * rinv) * bf_lo(p4.y); d0[3] = fast_sigmoid(d0[3] * rinv) * bf_hi(p4.y);
;                             d1[0] = fast_sigmoid(d1[0] * rinv) * bf_lo(p4.z); d1[1] = fast_sigmoid(d1[1] * rinv) * bf_hi(p4.z);
;                             d1[2] = fast_sigmoid(d1[2] * rinv) * bf_lo(p4.w); d1[3] = fast_sigmoid(d1[3] * rinv) * bf_hi(p4.w); }
;                         a += d0; b += d1;
;                         u32x4 w; w.x = pg8::cvt_pk_bf16(a[0], a[1]); w.y = pg8::cvt_pk_bf16(a[2], a[3]); w.z = pg8::cvt_pk_bf16(b[0], b[1]); w.w = pg8::cvt_pk_bf16(b[2], b[3]);
;                         *(u32x4*)(O + off) = w;
;                         ss += (a[0] * a[0] + a[1] * a[1]) + (a[2] * a[2] + a[3] * a[3]) + (b[0] * b[0] + b[1] * b[1]) + (b[2] * b[2] + b[3] * b[3]); }
;                     ss = xrow16_sum(ss);
;                     if (fq == 0) part_out[(size_t)row * 16 + u.pn * 4 + wc] = ss;
.LBB0_577:
	s_or_b64 exec, exec, s[28:29]
	v_add_u32_e32 v114, 32, v146
	v_ashrrev_i32_e32 v115, 31, v114
	v_lshlrev_b64 v[96:97], 10, v[114:115]
	v_lshl_add_u64 v[96:97], v[96:97], 0, v[144:145]
	v_readlane_b32 s28, v255, 24
	v_lshlrev_b64 v[96:97], 1, v[96:97]
	v_readlane_b32 s29, v255, 25
	v_add_f32_e32 v100, v160, v161
	v_add_u32_e32 v112, 48, v146
	v_lshl_add_u64 v[98:99], s[28:29], 0, v[96:97]
	v_lshl_add_u64 v[96:97], s[74:75], 0, v[96:97]
	global_load_dwordx4 v[116:119], v[98:99], off nt
	global_load_dwordx4 v[120:123], v[96:97], off nt
	v_fmamk_f32 v100, v100, 0x3a800000, v233
	v_ashrrev_i32_e32 v113, 31, v112
	v_rsq_f32_e32 v142, v100
	v_lshlrev_b64 v[100:101], 10, v[112:113]
	v_lshl_add_u64 v[100:101], v[100:101], 0, v[144:145]
	v_lshlrev_b64 v[100:101], 1, v[100:101]
	v_lshl_add_u64 v[102:103], s[28:29], 0, v[100:101]
	v_lshl_add_u64 v[134:135], s[74:75], 0, v[100:101]
	global_load_dwordx4 v[124:127], v[98:99], off offset:256 nt
	global_load_dwordx4 v[128:131], v[96:97], off offset:256 nt
	global_load_dwordx4 v[108:111], v[102:103], off nt
	s_nop 0
	global_load_dwordx4 v[100:103], v[102:103], off offset:256 nt
	s_nop 0
	global_load_dwordx4 v[104:107], v[134:135], off nt
	global_load_dwordx4 v[96:99], v[134:135], off offset:256 nt
	v_mul_f32_e32 v94, v94, v142
	v_mul_f32_e32 v95, v95, v142
	v_mul_f32_e32 v90, v90, v142
	v_mul_f32_e32 v91, v91, v142
	v_mul_f32_e32 v92, v92, v142
	v_mul_f32_e32 v93, v93, v142
	v_mul_f32_e32 v94, 0xbfb8aa3b, v94
	v_mul_f32_e32 v95, 0xbfb8aa3b, v95
	v_mul_f32_e32 v90, 0xbfb8aa3b, v90
	v_mul_f32_e32 v91, 0xbfb8aa3b, v91
	v_mul_f32_e32 v88, v88, v142
	v_mul_f32_e32 v89, v89, v142
	v_mul_f32_e32 v92, 0xbfb8aa3b, v92
	v_mul_f32_e32 v93, 0xbfb8aa3b, v93
	v_exp_f32_e32 v94, v94
	v_exp_f32_e32 v95, v95
	v_exp_f32_e32 v90, v90
	v_exp_f32_e32 v91, v91
	v_mul_f32_e32 v88, 0xbfb8aa3b, v88
	v_mul_f32_e32 v89, 0xbfb8aa3b, v89
	v_exp_f32_e32 v92, v92
	v_exp_f32_e32 v93, v93
	v_exp_f32_e32 v88, v88
	v_exp_f32_e32 v89, v89
	v_add_f32_e32 v94, 1.0, v94
	v_add_f32_e32 v95, 1.0, v95
	v_add_f32_e32 v136, 1.0, v90
	v_add_f32_e32 v137, 1.0, v91
	v_add_f32_e32 v92, 1.0, v92
	v_add_f32_e32 v93, 1.0, v93
	v_rcp_f32_e32 v90, v94
	v_rcp_f32_e32 v91, v95
	v_rcp_f32_e32 v94, v136
	v_rcp_f32_e32 v95, v137
	v_add_f32_e32 v134, 1.0, v88
	v_add_f32_e32 v135, 1.0, v89
	v_rcp_f32_e32 v88, v92
	v_rcp_f32_e32 v89, v93
	v_rcp_f32_e32 v92, v134
	v_rcp_f32_e32 v93, v135
	v_mul_f32_e32 v84, v84, v142
	v_mul_f32_e32 v85, v85, v142
	v_mul_f32_e32 v86, v86, v142
	v_mul_f32_e32 v87, v87, v142
	v_mul_f32_e32 v80, v80, v142
	v_mul_f32_e32 v81, v81, v142
	v_lshlrev_b64 v[132:133], 11, v[114:115]
	v_mul_f32_e32 v84, 0xbfb8aa3b, v84
	v_mul_f32_e32 v85, 0xbfb8aa3b, v85
	v_mul_f32_e32 v86, 0xbfb8aa3b, v86
	v_mul_f32_e32 v87, 0xbfb8aa3b, v87
	v_mul_f32_e32 v80, 0xbfb8aa3b, v80
	v_mul_f32_e32 v81, 0xbfb8aa3b, v81
	v_mul_f32_e32 v82, v82, v142
	v_mul_f32_e32 v83, v83, v142
	v_exp_f32_e32 v84, v84
	v_exp_f32_e32 v85, v85
	v_exp_f32_e32 v86, v86
	v_exp_f32_e32 v87, v87
	v_exp_f32_e32 v80, v80
	v_exp_f32_e32 v81, v81
	v_mul_f32_e32 v82, 0xbfb8aa3b, v82
	v_mul_f32_e32 v83, 0xbfb8aa3b, v83
	v_exp_f32_e32 v82, v82
	v_exp_f32_e32 v83, v83
	v_add_f32_e32 v84, 1.0, v84
	v_add_f32_e32 v85, 1.0, v85
	v_add_f32_e32 v86, 1.0, v86
	v_add_f32_e32 v87, 1.0, v87
	s_waitcnt vmcnt(0)
	v_lshlrev_b32_e32 v136, 16, v118
	v_and_b32_e32 v137, 0xffff0000, v118
	v_lshlrev_b32_e32 v118, 16, v119
	v_and_b32_e32 v119, 0xffff0000, v119
	v_lshlrev_b32_e32 v140, 16, v122
	v_and_b32_e32 v141, 0xffff0000, v122
	v_lshlrev_b32_e32 v122, 16, v123
	v_and_b32_e32 v123, 0xffff0000, v123
	v_lshlrev_b32_e32 v134, 16, v116
	v_and_b32_e32 v135, 0xffff0000, v116
	v_lshlrev_b32_e32 v116, 16, v117
	v_and_b32_e32 v117, 0xffff0000, v117
	v_lshlrev_b32_e32 v138, 16, v120
	v_and_b32_e32 v139, 0xffff0000, v120
	v_lshlrev_b32_e32 v120, 16, v121
	v_and_b32_e32 v121, 0xffff0000, v121
	v_pk_fma_f32 v[94:95], v[94:95], v[122:123], v[118:119]
	v_lshl_add_u64 v[118:119], s[20:21], 0, v[132:133]
	v_pk_fma_f32 v[116:117], v[90:91], v[120:121], v[116:117]
	v_pk_fma_f32 v[120:121], v[88:89], v[138:139], v[134:135]
	v_lshl_add_u64 v[118:119], v[144:145], 1, v[118:119]
	v_cvt_pk_bf16_f32 v88, v120, v121
	v_cvt_pk_bf16_f32 v89, v116, v117
	v_pk_fma_f32 v[92:93], v[92:93], v[140:141], v[136:137]
	v_add_f32_e32 v80, 1.0, v80
	v_cvt_pk_bf16_f32 v90, v92, v93
	v_cvt_pk_bf16_f32 v91, v94, v95
	global_store_dwordx4 v[118:119], v[88:91], off
	v_add_f32_e32 v81, 1.0, v81
	v_rcp_f32_e32 v84, v84
	v_mul_f32_e32 v88, v121, v121
	v_mul_f32_e32 v89, v117, v117
	v_fmac_f32_e32 v88, v120, v120
	v_fmac_f32_e32 v89, v116, v116
	v_add_f32_e32 v88, v88, v89
	v_mul_f32_e32 v89, v93, v93
	v_fmac_f32_e32 v89, v92, v92
	v_rcp_f32_e32 v85, v85
	v_rcp_f32_e32 v86, v86
	v_rcp_f32_e32 v87, v87
	v_rcp_f32_e32 v80, v80
	v_rcp_f32_e32 v81, v81
	v_add_f32_e32 v82, 1.0, v82
	v_add_f32_e32 v83, 1.0, v83
	v_add_f32_e32 v88, v89, v88
	v_mul_f32_e32 v89, v95, v95
	v_rcp_f32_e32 v82, v82
	v_rcp_f32_e32 v83, v83
	v_fmac_f32_e32 v89, v94, v94
	v_add_f32_e32 v132, v89, v88
	v_lshlrev_b32_e32 v88, 16, v124
	v_and_b32_e32 v89, 0xffff0000, v124
	v_lshlrev_b32_e32 v90, 16, v125
	v_and_b32_e32 v91, 0xffff0000, v125
	v_lshlrev_b32_e32 v92, 16, v126
	v_and_b32_e32 v93, 0xffff0000, v126
	v_lshlrev_b32_e32 v116, 16, v128
	v_and_b32_e32 v117, 0xffff0000, v128
	v_lshlrev_b32_e32 v120, 16, v129
	v_and_b32_e32 v121, 0xffff0000, v129
	v_lshlrev_b32_e32 v122, 16, v130
	v_and_b32_e32 v123, 0xffff0000, v130
	v_lshlrev_b32_e32 v94, 16, v127
	v_and_b32_e32 v95, 0xffff0000, v127
	v_lshlrev_b32_e32 v124, 16, v131
	v_and_b32_e32 v125, 0xffff0000, v131
	v_pk_fma_f32 v[86:87], v[86:87], v[120:121], v[90:91]
	v_pk_fma_f32 v[84:85], v[84:85], v[116:117], v[88:89]
	v_pk_fma_f32 v[90:91], v[80:81], v[122:123], v[92:93]
	v_cvt_pk_bf16_f32 v80, v84, v85
	v_cvt_pk_bf16_f32 v81, v86, v87
	v_pk_fma_f32 v[88:89], v[82:83], v[124:125], v[94:95]
	v_cvt_pk_bf16_f32 v82, v90, v91
	s_nop 0
	v_cvt_pk_bf16_f32 v83, v88, v89
	global_store_dwordx4 v[118:119], v[80:83], off offset:256
	s_nop 1
	v_mul_f32_e32 v80, v85, v85
	v_mul_f32_e32 v81, v87, v87
	v_fmac_f32_e32 v80, v84, v84
	v_fmac_f32_e32 v81, v86, v86
	v_add_f32_e32 v80, v80, v81
	v_mul_f32_e32 v81, v91, v91
	v_fmac_f32_e32 v81, v90, v90
	v_add_f32_e32 v80, v81, v80
	v_mul_f32_e32 v81, v89, v89
	v_fmac_f32_e32 v81, v88, v88
	v_add_f32_e32 v80, v81, v80
	v_add_f32_e32 v80, v132, v80
	v_mov_b32_e32 v81, v80
	s_nop 1
	v_permlane16_swap_b32_e32 v80, v81
	v_add_f32_e32 v80, v80, v81
	v_mov_b32_e32 v81, v80
	s_nop 1
	v_permlane32_swap_b32_e32 v80, v81
	s_and_saveexec_b64 s[28:29], vcc
	s_cbranch_execz .LBB0_579
	v_lshlrev_b64 v[82:83], 6, v[114:115]
	v_lshl_add_u64 v[82:83], s[18:19], 0, v[82:83]
	v_lshl_add_u64 v[82:83], s[0:1], 2, v[82:83]
	s_lshl_b32 s86, s49, 2
	v_lshl_add_u64 v[82:83], v[82:83], 0, s[86:87]
	v_add_f32_e32 v80, v80, v81
	flat_store_dword v[82:83], v80

;     __device__ __forceinline__ void operator()(const f32x4 (&acc)[2][2][4][2], const pg8::Unit& u, int wr, int wc, int fr_, int fq_, LAS const unsigned char* xl) const {
;     ...
;                 u32x4 hw[MB][2], pw[MB][2];
; #pragma unroll
;                 for (int m = 0; m < MB; ++m)
; #pragma unroll
;                     for (int bj = 0; bj < 2; ++bj) { const size_t off = (size_t)(row0 + ai * 128 + (mb + m) * 16) * DM + col + bj * 128;
;                         hw[m][bj] = *(const u32x4*)(h_old + off); if (MODE == 4) pw[m][bj] = *(const u32x4*)(pp + off); }
; #pragma unroll
;                 for (int mm = 0; mm < MB; ++mm) {
;                     const int m = mb + mm;
;                     const int row = row0 + ai * 128 + m * 16; const float rinv = rv[ai][m];
;                     float ss = 0.f;
; #pragma unroll
;                     for (int bj = 0; bj < 2; ++bj) { const size_t off = (size_t)row * DM + col + bj * 128;
;                         const u32x4 h4 = hw[mm][bj];
;                         f32x4 a = {bf_lo(h4.x), bf_hi(h4.x), bf_lo(h4.y), bf_hi(h4.y)}, b = {bf_lo(h4.z), bf_hi(h4.z), bf_lo(h4.w), bf_hi(h4.w)};
;                         f32x4 d0 = acc[ai][bj][m][0], d1 = acc[ai][bj][m][1];
;                         if (MODE == 4) { const u32x4 p4 = pw[mm][bj];
;                             d0[0] = fast_sigmoid(d0[0] * rinv) * bf_lo(p4.x); d0[1] = fast_sigmoid(d0[1] * rinv) * bf_hi(p4.x);
;                             d0[2] = fast_sigmoid(d0[2] * rinv) * bf_lo(p4.y); d0[3] = fast_sigmoid(d0[3] * rinv) * bf_hi(p4.y);
;                             d1[0] = fast_sigmoid(d1[0] * rinv) * bf_lo(p4.z); d1[1] = fast_sigmoid(d1[1] * rinv) * bf_hi(p4.z);
;                             d1[2] = fast_sigmoid(d1[2] * rinv) * bf_lo(p4.w); d1[3] = fast_sigmoid(d1[3] * rinv) * bf_hi(p4.w); }
;                         a += d0; b += d1;
;                         u32x4 w; w.x = pg8::cvt_pk_bf16(a[0], a[1]); w.y = pg8::cvt_pk_bf16(a[2], a[3]); w.z = pg8::cvt_pk_bf16(b[0], b[1]); w.w = pg8::cvt_pk_bf16(b[2], b[3]);
;                         *(u32x4*)(O + off) = w;
;                         ss += (a[0] * a[0] + a[1] * a[1]) + (a[2] * a[2] + a[3] * a[3]) + (b[0] * b[0] + b[1] * b[1]) + (b[2] * b[2] + b[3] * b[3]); }
;                     ss = xrow16_sum(ss);
;                     if (fq == 0) part_out[(size_t)row * 16 + u.pn * 4 + wc] = ss;
.LBB0_581:
	s_or_b64 exec, exec, s[28:29]
	v_add_u32_e32 v82, 0x80, v146
	v_ashrrev_i32_e32 v83, 31, v82
	v_lshlrev_b64 v[64:65], 10, v[82:83]
	v_lshl_add_u64 v[64:65], v[64:65], 0, v[144:145]
	v_readlane_b32 s28, v255, 24
	v_lshlrev_b64 v[64:65], 1, v[64:65]
	v_readlane_b32 s29, v255, 25
	v_add_f32_e32 v68, v156, v157
	v_add_u32_e32 v80, 0x90, v146
	v_lshl_add_u64 v[66:67], s[28:29], 0, v[64:65]
	v_lshl_add_u64 v[64:65], s[74:75], 0, v[64:65]
	global_load_dwordx4 v[84:87], v[66:67], off nt
	global_load_dwordx4 v[88:91], v[64:65], off nt
	v_fmamk_f32 v68, v68, 0x3a800000, v233
	v_ashrrev_i32_e32 v81, 31, v80
	v_rsq_f32_e32 v110, v68
	v_lshlrev_b64 v[68:69], 10, v[80:81]
	v_lshl_add_u64 v[68:69], v[68:69], 0, v[144:145]
	v_lshlrev_b64 v[68:69], 1, v[68:69]
	v_lshl_add_u64 v[70:71], s[28:29], 0, v[68:69]
	v_lshl_add_u64 v[102:103], s[74:75], 0, v[68:69]
	global_load_dwordx4 v[92:95], v[66:67], off offset:256 nt
	global_load_dwordx4 v[96:99], v[64:65], off offset:256 nt
	global_load_dwordx4 v[76:79], v[70:71], off nt
	s_nop 0
	global_load_dwordx4 v[68:71], v[70:71], off offset:256 nt
	s_nop 0
	global_load_dwordx4 v[72:75], v[102:103], off nt
	global_load_dwordx4 v[64:67], v[102:103], off offset:256 nt
	v_mul_f32_e32 v62, v62, v110
	v_mul_f32_e32 v63, v63, v110
	v_mul_f32_e32 v58, v58, v110
	v_mul_f32_e32 v59, v59, v110
	v_mul_f32_e32 v60, v60, v110
	v_mul_f32_e32 v61, v61, v110
	v_mul_f32_e32 v62, 0xbfb8aa3b, v62
	v_mul_f32_e32 v63, 0xbfb8aa3b, v63
	v_mul_f32_e32 v58, 0xbfb8aa3b, v58
	v_mul_f32_e32 v59, 0xbfb8aa3b, v59
	v_mul_f32_e32 v56, v56, v110
	v_mul_f32_e32 v57, v57, v110
	v_mul_f32_e32 v60, 0xbfb8aa3b, v60
	v_mul_f32_e32 v61, 0xbfb8aa3b, v61
	v_exp_f32_e32 v62, v62
	v_exp_f32_e32 v63, v63
	v_exp_f32_e32 v58, v58
	v_exp_f32_e32 v59, v59
	v_mul_f32_e32 v56, 0xbfb8aa3b, v56
	v_mul_f32_e32 v57, 0xbfb8aa3b, v57
	v_exp_f32_e32 v60, v60
	v_exp_f32_e32 v61, v61
	v_exp_f32_e32 v56, v56
	v_exp_f32_e32 v57, v57
	v_add_f32_e32 v62, 1.0, v62
	v_add_f32_e32 v63, 1.0, v63
	v_add_f32_e32 v104, 1.0, v58
	v_add_f32_e32 v105, 1.0, v59
	v_add_f32_e32 v60, 1.0, v60
	v_add_f32_e32 v61, 1.0, v61
	v_rcp_f32_e32 v58, v62
	v_rcp_f32_e32 v59, v63
	v_rcp_f32_e32 v62, v104
	v_rcp_f32_e32 v63, v105
	v_add_f32_e32 v102, 1.0, v56
	v_add_f32_e32 v103, 1.0, v57
	v_rcp_f32_e32 v56, v60
	v_rcp_f32_e32 v57, v61
	v_rcp_f32_e32 v60, v102
	v_rcp_f32_e32 v61, v103
	v_mul_f32_e32 v52, v52, v110
	v_mul_f32_e32 v53, v53, v110
	v_mul_f32_e32 v54, v54, v110
	v_mul_f32_e32 v55, v55, v110
	v_mul_f32_e32 v48, v48, v110
	v_mul_f32_e32 v49, v49, v110
	v_lshlrev_b64 v[100:101], 11, v[82:83]
	v_mul_f32_e32 v52, 0xbfb8aa3b, v52
	v_mul_f32_e32 v53, 0xbfb8aa3b, v53
	v_mul_f32_e32 v54, 0xbfb8aa3b, v54
	v_mul_f32_e32 v55, 0xbfb8aa3b, v55
	v_mul_f32_e32 v48, 0xbfb8aa3b, v48
	v_mul_f32_e32 v49, 0xbfb8aa3b, v49
	v_mul_f32_e32 v50, v50, v110
	v_mul_f32_e32 v51, v51, v110
	v_exp_f32_e32 v52, v52
	v_exp_f32_e32 v53, v53
	v_exp_f32_e32 v54, v54
	v_exp_f32_e32 v55, v55
	v_exp_f32_e32 v48, v48
	v_exp_f32_e32 v49, v49
	v_mul_f32_e32 v50, 0xbfb8aa3b, v50
	v_mul_f32_e32 v51, 0xbfb8aa3b, v51
	v_exp_f32_e32 v50, v50
	v_exp_f32_e32 v51, v51
	v_add_f32_e32 v52, 1.0, v52
	v_add_f32_e32 v53, 1.0, v53
	v_add_f32_e32 v54, 1.0, v54
	v_add_f32_e32 v55, 1.0, v55
	s_waitcnt vmcnt(0)
	v_lshlrev_b32_e32 v104, 16, v86
	v_and_b32_e32 v105, 0xffff0000, v86
	v_lshlrev_b32_e32 v86, 16, v87
	v_and_b32_e32 v87, 0xffff0000, v87
	v_lshlrev_b32_e32 v108, 16, v90
	v_and_b32_e32 v109, 0xffff0000, v90
	v_lshlrev_b32_e32 v90, 16, v91
	v_and_b32_e32 v91, 0xffff0000, v91
	v_lshlrev_b32_e32 v102, 16, v84
	v_and_b32_e32 v103, 0xffff0000, v84
	v_lshlrev_b32_e32 v84, 16, v85
	v_and_b32_e32 v85, 0xffff0000, v85
	v_lshlrev_b32_e32 v106, 16, v88
	v_and_b32_e32 v107, 0xffff0000, v88
	v_lshlrev_b32_e32 v88, 16, v89
	v_and_b32_e32 v89, 0xffff0000, v89
	v_pk_fma_f32 v[62:63], v[62:63], v[90:91], v[86:87]
	v_lshl_add_u64 v[86:87], s[20:21], 0, v[100:101]
	v_pk_fma_f32 v[84:85], v[58:59], v[88:89], v[84:85]
	v_pk_fma_f32 v[88:89], v[56:57], v[106:107], v[102:103]
	v_lshl_add_u64 v[86:87], v[144:145], 1, v[86:87]
	v_cvt_pk_bf16_f32 v56, v88, v89
	v_cvt_pk_bf16_f32 v57, v84, v85
	v_pk_fma_f32 v[60:61], v[60:61], v[108:109], v[104:105]
	v_add_f32_e32 v48, 1.0, v48
	v_cvt_pk_bf16_f32 v58, v60, v61
	v_cvt_pk_bf16_f32 v59, v62, v63
	global_store_dwordx4 v[86:87], v[56:59], off
	v_add_f32_e32 v49, 1.0, v49
	v_rcp_f32_e32 v52, v52
	v_mul_f32_e32 v56, v89, v89
	v_mul_f32_e32 v57, v85, v85
	v_fmac_f32_e32 v56, v88, v88
	v_fmac_f32_e32 v57, v84, v84
	v_add_f32_e32 v56, v56, v57
	v_mul_f32_e32 v57, v61, v61
	v_fmac_f32_e32 v57, v60, v60
	v_rcp_f32_e32 v53, v53
	v_rcp_f32_e32 v54, v54
	v_rcp_f32_e32 v55, v55
	v_rcp_f32_e32 v48, v48
	v_rcp_f32_e32 v49, v49
	v_add_f32_e32 v50, 1.0, v50
	v_add_f32_e32 v51, 1.0, v51
	v_add_f32_e32 v56, v57, v56
	v_mul_f32_e32 v57, v63, v63
	v_rcp_f32_e32 v50, v50
	v_rcp_f32_e32 v51, v51
	v_fmac_f32_e32 v57, v62, v62
	v_add_f32_e32 v100, v57, v56
	v_lshlrev_b32_e32 v56, 16, v92
	v_and_b32_e32 v57, 0xffff0000, v92
	v_lshlrev_b32_e32 v58, 16, v93
	v_and_b32_e32 v59, 0xffff0000, v93
	v_lshlrev_b32_e32 v60, 16, v94
	v_and_b32_e32 v61, 0xffff0000, v94
	v_lshlrev_b32_e32 v84, 16, v96
	v_and_b32_e32 v85, 0xffff0000, v96
	v_lshlrev_b32_e32 v88, 16, v97
	v_and_b32_e32 v89, 0xffff0000, v97
	v_lshlrev_b32_e32 v90, 16, v98
	v_and_b32_e32 v91, 0xffff0000, v98
	v_lshlrev_b32_e32 v62, 16, v95
	v_and_b32_e32 v63, 0xffff0000, v95
	v_lshlrev_b32_e32 v92, 16, v99
	v_and_b32_e32 v93, 0xffff0000, v99
	v_pk_fma_f32 v[54:55], v[54:55], v[88:89], v[58:59]
	v_pk_fma_f32 v[52:53], v[52:53], v[84:85], v[56:57]
	v_pk_fma_f32 v[58:59], v[48:49], v[90:91], v[60:61]
	v_cvt_pk_bf16_f32 v48, v52, v53
	v_cvt_pk_bf16_f32 v49, v54, v55
	v_pk_fma_f32 v[56:57], v[50:51], v[92:93], v[62:63]
	v_cvt_pk_bf16_f32 v50, v58, v59
	s_nop 0
	v_cvt_pk_bf16_f32 v51, v56, v57
	global_store_dwordx4 v[86:87], v[48:51], off offset:256
	s_nop 1
	v_mul_f32_e32 v48, v53, v53
	v_mul_f32_e32 v49, v55, v55
	v_fmac_f32_e32 v48, v52, v52
	v_fmac_f32_e32 v49, v54, v54
	v_add_f32_e32 v48, v48, v49
	v_mul_f32_e32 v49, v59, v59
	v_fmac_f32_e32 v49, v58, v58
	v_add_f32_e32 v48, v49, v48
	v_mul_f32_e32 v49, v57, v57
	v_fmac_f32_e32 v49, v56, v56
	v_add_f32_e32 v48, v49, v48
	v_add_f32_e32 v48, v100, v48
	v_mov_b32_e32 v49, v48
	s_nop 1
	v_permlane16_swap_b32_e32 v48, v49
	v_add_f32_e32 v48, v48, v49
	v_mov_b32_e32 v49, v48
	s_nop 1
	v_permlane32_swap_b32_e32 v48, v49
	s_and_saveexec_b64 s[28:29], vcc
	s_cbranch_execz .LBB0_583
	v_lshlrev_b64 v[50:51], 6, v[82:83]
	v_lshl_add_u64 v[50:51], s[18:19], 0, v[50:51]
	v_lshl_add_u64 v[50:51], s[0:1], 2, v[50:51]
	s_lshl_b32 s86, s49, 2
	v_lshl_add_u64 v[50:51], v[50:51], 0, s[86:87]
	v_add_f32_e32 v48, v48, v49
	flat_store_dword v[50:51], v48

;     __device__ __forceinline__ void operator()(const f32x4 (&acc)[2][2][4][2], const pg8::Unit& u, int wr, int wc, int fr_, int fq_, LAS const unsigned char* xl) const {
;     ...
;                 u32x4 hw[MB][2], pw[MB][2];
; #pragma unroll
;                 for (int m = 0; m < MB; ++m)
; #pragma unroll
;                     for (int bj = 0; bj < 2; ++bj) { const size_t off = (size_t)(row0 + ai * 128 + (mb + m) * 16) * DM + col + bj * 128;
;                         hw[m][bj] = *(const u32x4*)(h_old + off); if (MODE == 4) pw[m][bj] = *(const u32x4*)(pp + off); }
; #pragma unroll
;                 for (int mm = 0; mm < MB; ++mm) {
;                     const int m = mb + mm;
;                     const int row = row0 + ai * 128 + m * 16; const float rinv = rv[ai][m];
;                     float ss = 0.f;
; #pragma unroll
;                     for (int bj = 0; bj < 2; ++bj) { const size_t off = (size_t)row * DM + col + bj * 128;
;                         const u32x4 h4 = hw[mm][bj];
;                         f32x4 a = {bf_lo(h4.x), bf_hi(h4.x), bf_lo(h4.y), bf_hi(h4.y)}, b = {bf_lo(h4.z), bf_hi(h4.z), bf_lo(h4.w), bf_hi(h4.w)};
;                         f32x4 d0 = acc[ai][bj][m][0], d1 = acc[ai][bj][m][1];
;                         if (MODE == 4) { const u32x4 p4 = pw[mm][bj];
;                             d0[0] = fast_sigmoid(d0[0] * rinv) * bf_lo(p4.x); d0[1] = fast_sigmoid(d0[1] * rinv) * bf_hi(p4.x);
;                             d0[2] = fast_sigmoid(d0[2] * rinv) * bf_lo(p4.y); d0[3] = fast_sigmoid(d0[3] * rinv) * bf_hi(p4.y);
;                             d1[0] = fast_sigmoid(d1[0] * rinv) * bf_lo(p4.z); d1[1] = fast_sigmoid(d1[1] * rinv) * bf_hi(p4.z);
;                             d1[2] = fast_sigmoid(d1[2] * rinv) * bf_lo(p4.w); d1[3] = fast_sigmoid(d1[3] * rinv) * bf_hi(p4.w); }
;                         a += d0; b += d1;
;                         u32x4 w; w.x = pg8::cvt_pk_bf16(a[0], a[1]); w.y = pg8::cvt_pk_bf16(a[2], a[3]); w.z = pg8::cvt_pk_bf16(b[0], b[1]); w.w = pg8::cvt_pk_bf16(b[2], b[3]);
;                         *(u32x4*)(O + off) = w;
;                         ss += (a[0] * a[0] + a[1] * a[1]) + (a[2] * a[2] + a[3] * a[3]) + (b[0] * b[0] + b[1] * b[1]) + (b[2] * b[2] + b[3] * b[3]); }
;                     ss = xrow16_sum(ss);
;                     if (fq == 0) part_out[(size_t)row * 16 + u.pn * 4 + wc] = ss;
.LBB0_585:
	s_or_b64 exec, exec, s[28:29]
	v_add_u32_e32 v50, 0xa0, v146
	v_ashrrev_i32_e32 v51, 31, v50
	v_lshlrev_b64 v[32:33], 10, v[50:51]
	v_lshl_add_u64 v[32:33], v[32:33], 0, v[144:145]
	v_readlane_b32 s28, v255, 24
	v_lshlrev_b64 v[32:33], 1, v[32:33]
	v_readlane_b32 s29, v255, 25
	v_add_f32_e32 v36, v152, v153
	v_add_u32_e32 v48, 0xb0, v146
	v_lshl_add_u64 v[34:35], s[28:29], 0, v[32:33]
	v_lshl_add_u64 v[32:33], s[74:75], 0, v[32:33]
	global_load_dwordx4 v[52:55], v[34:35], off nt
	global_load_dwordx4 v[56:59], v[32:33], off nt
	v_fmamk_f32 v36, v36, 0x3a800000, v233
	v_ashrrev_i32_e32 v49, 31, v48
	v_rsq_f32_e32 v78, v36
	v_lshlrev_b64 v[36:37], 10, v[48:49]
	v_lshl_add_u64 v[36:37], v[36:37], 0, v[144:145]
	v_lshlrev_b64 v[36:37], 1, v[36:37]
	v_lshl_add_u64 v[38:39], s[28:29], 0, v[36:37]
	v_lshl_add_u64 v[70:71], s[74:75], 0, v[36:37]
	global_load_dwordx4 v[60:63], v[34:35], off offset:256 nt
	global_load_dwordx4 v[64:67], v[32:33], off offset:256 nt
	global_load_dwordx4 v[44:47], v[38:39], off nt
	s_nop 0
	global_load_dwordx4 v[36:39], v[38:39], off offset:256 nt
	s_nop 0
	global_load_dwordx4 v[40:43], v[70:71], off nt
	global_load_dwordx4 v[32:35], v[70:71], off offset:256 nt
	v_mul_f32_e32 v30, v30, v78
	v_mul_f32_e32 v31, v31, v78
	v_mul_f32_e32 v26, v26, v78
	v_mul_f32_e32 v27, v27, v78
	v_mul_f32_e32 v28, v28, v78
	v_mul_f32_e32 v29, v29, v78
	v_mul_f32_e32 v30, 0xbfb8aa3b, v30
	v_mul_f32_e32 v31, 0xbfb8aa3b, v31
	v_mul_f32_e32 v26, 0xbfb8aa3b, v26
	v_mul_f32_e32 v27, 0xbfb8aa3b, v27
	v_mul_f32_e32 v24, v24, v78
	v_mul_f32_e32 v25, v25, v78
	v_mul_f32_e32 v28, 0xbfb8aa3b, v28
	v_mul_f32_e32 v29, 0xbfb8aa3b, v29
	v_exp_f32_e32 v30, v30
	v_exp_f32_e32 v31, v31
	v_exp_f32_e32 v26, v26
	v_exp_f32_e32 v27, v27
	v_mul_f32_e32 v24, 0xbfb8aa3b, v24
	v_mul_f32_e32 v25, 0xbfb8aa3b, v25
	v_exp_f32_e32 v28, v28
	v_exp_f32_e32 v29, v29
	v_exp_f32_e32 v24, v24
	v_exp_f32_e32 v25, v25
	v_add_f32_e32 v30, 1.0, v30
	v_add_f32_e32 v31, 1.0, v31
	v_add_f32_e32 v72, 1.0, v26
	v_add_f32_e32 v73, 1.0, v27
	v_add_f32_e32 v28, 1.0, v28
	v_add_f32_e32 v29, 1.0, v29
	v_rcp_f32_e32 v26, v30
	v_rcp_f32_e32 v27, v31
	v_rcp_f32_e32 v30, v72
	v_rcp_f32_e32 v31, v73
	v_add_f32_e32 v70, 1.0, v24
	v_add_f32_e32 v71, 1.0, v25
	v_rcp_f32_e32 v24, v28
	v_rcp_f32_e32 v25, v29
	v_rcp_f32_e32 v28, v70
	v_rcp_f32_e32 v29, v71
	v_mul_f32_e32 v20, v20, v78
	v_mul_f32_e32 v21, v21, v78
	v_mul_f32_e32 v22, v22, v78
	v_mul_f32_e32 v23, v23, v78
	v_mul_f32_e32 v16, v16, v78
	v_mul_f32_e32 v17, v17, v78
	v_lshlrev_b64 v[68:69], 11, v[50:51]
	v_mul_f32_e32 v20, 0xbfb8aa3b, v20
	v_mul_f32_e32 v21, 0xbfb8aa3b, v21
	v_mul_f32_e32 v22, 0xbfb8aa3b, v22
	v_mul_f32_e32 v23, 0xbfb8aa3b, v23
	v_mul_f32_e32 v16, 0xbfb8aa3b, v16
	v_mul_f32_e32 v17, 0xbfb8aa3b, v17
	v_mul_f32_e32 v18, v18, v78
	v_mul_f32_e32 v19, v19, v78
	v_exp_f32_e32 v20, v20
	v_exp_f32_e32 v21, v21
	v_exp_f32_e32 v22, v22
	v_exp_f32_e32 v23, v23
	v_exp_f32_e32 v16, v16
	v_exp_f32_e32 v17, v17
	v_mul_f32_e32 v18, 0xbfb8aa3b, v18
	v_mul_f32_e32 v19, 0xbfb8aa3b, v19
	v_exp_f32_e32 v18, v18
	v_exp_f32_e32 v19, v19
	v_add_f32_e32 v20, 1.0, v20
	v_add_f32_e32 v21, 1.0, v21
	v_add_f32_e32 v22, 1.0, v22
	v_add_f32_e32 v23, 1.0, v23
	s_waitcnt vmcnt(0)
	v_lshlrev_b32_e32 v72, 16, v54
	v_and_b32_e32 v73, 0xffff0000, v54
	v_lshlrev_b32_e32 v54, 16, v55
	v_and_b32_e32 v55, 0xffff0000, v55
	v_lshlrev_b32_e32 v76, 16, v58
	v_and_b32_e32 v77, 0xffff0000, v58
	v_lshlrev_b32_e32 v58, 16, v59
	v_and_b32_e32 v59, 0xffff0000, v59
	v_lshlrev_b32_e32 v70, 16, v52
	v_and_b32_e32 v71, 0xffff0000, v52
	v_lshlrev_b32_e32 v52, 16, v53
	v_and_b32_e32 v53, 0xffff0000, v53
	v_lshlrev_b32_e32 v74, 16, v56
	v_and_b32_e32 v75, 0xffff0000, v56
	v_lshlrev_b32_e32 v56, 16, v57
	v_and_b32_e32 v57, 0xffff0000, v57
	v_pk_fma_f32 v[30:31], v[30:31], v[58:59], v[54:55]
	v_lshl_add_u64 v[54:55], s[20:21], 0, v[68:69]
	v_pk_fma_f32 v[52:53], v[26:27], v[56:57], v[52:53]
	v_pk_fma_f32 v[56:57], v[24:25], v[74:75], v[70:71]
	v_lshl_add_u64 v[54:55], v[144:145], 1, v[54:55]
	v_cvt_pk_bf16_f32 v24, v56, v57
	v_cvt_pk_bf16_f32 v25, v52, v53
	v_pk_fma_f32 v[28:29], v[28:29], v[76:77], v[72:73]
	v_add_f32_e32 v16, 1.0, v16
	v_cvt_pk_bf16_f32 v26, v28, v29
	v_cvt_pk_bf16_f32 v27, v30, v31
	global_store_dwordx4 v[54:55], v[24:27], off
	v_add_f32_e32 v17, 1.0, v17
	v_rcp_f32_e32 v20, v20
	v_mul_f32_e32 v24, v57, v57
	v_mul_f32_e32 v25, v53, v53
	v_fmac_f32_e32 v24, v56, v56
	v_fmac_f32_e32 v25, v52, v52
	v_add_f32_e32 v24, v24, v25
	v_mul_f32_e32 v25, v29, v29
	v_fmac_f32_e32 v25, v28, v28
	v_rcp_f32_e32 v21, v21
	v_rcp_f32_e32 v22, v22
	v_rcp_f32_e32 v23, v23
	v_rcp_f32_e32 v16, v16
	v_rcp_f32_e32 v17, v17
	v_add_f32_e32 v18, 1.0, v18
	v_add_f32_e32 v19, 1.0, v19
	v_add_f32_e32 v24, v25, v24
	v_mul_f32_e32 v25, v31, v31
	v_rcp_f32_e32 v18, v18
	v_rcp_f32_e32 v19, v19
	v_fmac_f32_e32 v25, v30, v30
	v_add_f32_e32 v68, v25, v24
	v_lshlrev_b32_e32 v24, 16, v60
	v_and_b32_e32 v25, 0xffff0000, v60
	v_lshlrev_b32_e32 v26, 16, v61
	v_and_b32_e32 v27, 0xffff0000, v61
	v_lshlrev_b32_e32 v28, 16, v62
	v_and_b32_e32 v29, 0xffff0000, v62
	v_lshlrev_b32_e32 v52, 16, v64
	v_and_b32_e32 v53, 0xffff0000, v64
	v_lshlrev_b32_e32 v56, 16, v65
	v_and_b32_e32 v57, 0xffff0000, v65
	v_lshlrev_b32_e32 v58, 16, v66
	v_and_b32_e32 v59, 0xffff0000, v66
	v_lshlrev_b32_e32 v30, 16, v63
	v_and_b32_e32 v31, 0xffff0000, v63
	v_lshlrev_b32_e32 v60, 16, v67
	v_and_b32_e32 v61, 0xffff0000, v67
	v_pk_fma_f32 v[22:23], v[22:23], v[56:57], v[26:27]
	v_pk_fma_f32 v[20:21], v[20:21], v[52:53], v[24:25]
	v_pk_fma_f32 v[26:27], v[16:17], v[58:59], v[28:29]
	v_cvt_pk_bf16_f32 v16, v20, v21
	v_cvt_pk_bf16_f32 v17, v22, v23
	v_pk_fma_f32 v[24:25], v[18:19], v[60:61], v[30:31]
	v_cvt_pk_bf16_f32 v18, v26, v27
	s_nop 0
	v_cvt_pk_bf16_f32 v19, v24, v25
	global_store_dwordx4 v[54:55], v[16:19], off offset:256
	s_nop 1
	v_mul_f32_e32 v16, v21, v21
	v_mul_f32_e32 v17, v23, v23
	v_fmac_f32_e32 v16, v20, v20
	v_fmac_f32_e32 v17, v22, v22
	v_add_f32_e32 v16, v16, v17
	v_mul_f32_e32 v17, v27, v27
	v_fmac_f32_e32 v17, v26, v26
	v_add_f32_e32 v16, v17, v16
	v_mul_f32_e32 v17, v25, v25
	v_fmac_f32_e32 v17, v24, v24
	v_add_f32_e32 v16, v17, v16
	v_add_f32_e32 v16, v68, v16
	v_mov_b32_e32 v17, v16
	s_nop 1
	v_permlane16_swap_b32_e32 v16, v17
	v_add_f32_e32 v16, v16, v17
	v_mov_b32_e32 v17, v16
	s_nop 1
	v_permlane32_swap_b32_e32 v16, v17
	s_and_saveexec_b64 s[28:29], vcc
	s_cbranch_execz .LBB0_587
	v_lshlrev_b64 v[18:19], 6, v[50:51]
	v_lshl_add_u64 v[18:19], s[18:19], 0, v[18:19]
	v_lshl_add_u64 v[18:19], s[0:1], 2, v[18:19]
	s_lshl_b32 s86, s49, 2
	v_lshl_add_u64 v[18:19], v[18:19], 0, s[86:87]
	v_add_f32_e32 v16, v16, v17
	flat_store_dword v[18:19], v16
